# v13 + K-loops: closing barrier signalled before s_setprio 0
# baseline (speedup 1.0000x reference)
.Lg1_nopf:
	s_barrier
	v_mfma_f32_16x16x32_bf16 v[124:127], v[128:131], v[204:207], v[124:127]
	v_mfma_f32_16x16x32_bf16 v[120:123], v[136:139], v[204:207], v[120:123]
	v_mfma_f32_16x16x32_bf16 v[96:99], v[128:131], v[212:215], v[96:99]
	v_mfma_f32_16x16x32_bf16 v[88:91], v[136:139], v[212:215], v[88:91]
	v_mfma_f32_16x16x32_bf16 v[76:79], v[128:131], v[220:223], v[76:79]
	v_mfma_f32_16x16x32_bf16 v[72:75], v[136:139], v[220:223], v[72:75]
	v_mfma_f32_16x16x32_bf16 v[60:63], v[128:131], v[228:231], v[60:63]
	v_mfma_f32_16x16x32_bf16 v[108:111], v[136:139], v[228:231], v[108:111]
	v_mfma_f32_16x16x32_bf16 v[124:127], v[132:135], v[208:211], v[124:127]
	v_mfma_f32_16x16x32_bf16 v[120:123], v[158:161], v[208:211], v[120:123]
	v_mfma_f32_16x16x32_bf16 v[96:99], v[132:135], v[216:219], v[96:99]
	v_mfma_f32_16x16x32_bf16 v[88:91], v[158:161], v[216:219], v[88:91]
	v_mfma_f32_16x16x32_bf16 v[76:79], v[132:135], v[224:227], v[76:79]
	v_mfma_f32_16x16x32_bf16 v[72:75], v[158:161], v[224:227], v[72:75]
	v_mfma_f32_16x16x32_bf16 v[60:63], v[132:135], v[232:235], v[60:63]
	v_mfma_f32_16x16x32_bf16 v[108:111], v[158:161], v[232:235], v[108:111]
	s_setprio 0
	s_setprio 1
	v_mfma_f32_16x16x32_bf16 v[116:119], v[168:171], v[204:207], v[116:119]
	v_mfma_f32_16x16x32_bf16 v[112:115], v[196:199], v[204:207], v[112:115]
	v_mfma_f32_16x16x32_bf16 v[84:87], v[168:171], v[212:215], v[84:87]
	v_mfma_f32_16x16x32_bf16 v[80:83], v[196:199], v[212:215], v[80:83]
	v_mfma_f32_16x16x32_bf16 v[68:71], v[168:171], v[220:223], v[68:71]
	v_mfma_f32_16x16x32_bf16 v[64:67], v[196:199], v[220:223], v[64:67]
	v_mfma_f32_16x16x32_bf16 v[104:107], v[168:171], v[228:231], v[104:107]
	v_mfma_f32_16x16x32_bf16 v[56:59], v[196:199], v[228:231], v[56:59]
	v_mfma_f32_16x16x32_bf16 v[116:119], v[172:175], v[208:211], v[116:119]
	v_mfma_f32_16x16x32_bf16 v[112:115], v[200:203], v[208:211], v[112:115]
	v_mfma_f32_16x16x32_bf16 v[84:87], v[172:175], v[216:219], v[84:87]
	v_mfma_f32_16x16x32_bf16 v[80:83], v[200:203], v[216:219], v[80:83]
	v_mfma_f32_16x16x32_bf16 v[68:71], v[172:175], v[224:227], v[68:71]
	v_mfma_f32_16x16x32_bf16 v[64:67], v[200:203], v[224:227], v[64:67]
	v_mfma_f32_16x16x32_bf16 v[104:107], v[172:175], v[232:235], v[104:107]
	v_mfma_f32_16x16x32_bf16 v[56:59], v[200:203], v[232:235], v[56:59]
	s_barrier
	s_setprio 0
	s_add_i32 s87, s82, s23
	v_lshl_add_u64 v[162:163], s[66:67], 0, v[140:141]
	s_mov_b32 m0, s87
	ds_read_b128 v[204:207], v194 offset:16384
	ds_read_b128 v[208:211], v194 offset:17408
	ds_read_b128 v[212:215], v194 offset:18432
	ds_read_b128 v[216:219], v194 offset:19456
	ds_read_b128 v[220:223], v194 offset:20480
	ds_read_b128 v[224:227], v194 offset:21504
	ds_read_b128 v[228:231], v194 offset:22528
	ds_read_b128 v[232:235], v194 offset:23552
	global_load_lds_dwordx4 v[162:163], off
	s_add_i32 m0, s87, 0x2000
	s_add_u32 s88, s66, 0x40000
	v_lshl_add_u64 v[178:179], s[66:67], 0, v[142:143]
	s_addc_u32 s89, s67, 0
	s_add_i32 s87, s83, s23
	global_load_lds_dwordx4 v[178:179], off
	v_lshl_add_u64 v[184:185], s[88:89], 0, v[140:141]
	s_mov_b32 m0, s87
	v_lshl_add_u64 v[236:237], s[68:69], 0, v[142:143]
	global_load_lds_dwordx4 v[184:185], off
	v_lshl_add_u64 v[184:185], s[88:89], 0, v[142:143]
	s_add_i32 m0, s87, 0x2000
	s_nop 0
	global_load_lds_dwordx4 v[184:185], off
	v_lshl_add_u64 v[184:185], s[68:69], 0, v[140:141]
	s_mov_b32 m0, s70
	s_nop 0
	global_load_lds_dwordx4 v[184:185], off
	s_mov_b32 m0, s71
	s_nop 0
	global_load_lds_dwordx4 v[236:237], off
	s_waitcnt vmcnt(8)
	s_waitcnt lgkmcnt(0)
	s_setprio 1
	s_barrier
	v_mfma_f32_16x16x32_bf16 v[52:55], v[128:131], v[204:207], v[52:55]
	v_mfma_f32_16x16x32_bf16 v[48:51], v[136:139], v[204:207], v[48:51]
	v_mfma_f32_16x16x32_bf16 v[16:19], v[128:131], v[212:215], v[16:19]
	v_mfma_f32_16x16x32_bf16 v[8:11], v[136:139], v[212:215], v[8:11]
	v_mfma_f32_16x16x32_bf16 v[28:31], v[128:131], v[220:223], v[28:31]
	v_mfma_f32_16x16x32_bf16 v[24:27], v[136:139], v[220:223], v[24:27]
	v_mfma_f32_16x16x32_bf16 v[36:39], v[128:131], v[228:231], v[36:39]
	v_mfma_f32_16x16x32_bf16 v[100:103], v[136:139], v[228:231], v[100:103]
	v_mfma_f32_16x16x32_bf16 v[52:55], v[132:135], v[208:211], v[52:55]
	v_mfma_f32_16x16x32_bf16 v[48:51], v[158:161], v[208:211], v[48:51]
	v_mfma_f32_16x16x32_bf16 v[16:19], v[132:135], v[216:219], v[16:19]
	v_mfma_f32_16x16x32_bf16 v[8:11], v[158:161], v[216:219], v[8:11]
	v_mfma_f32_16x16x32_bf16 v[28:31], v[132:135], v[224:227], v[28:31]
	v_mfma_f32_16x16x32_bf16 v[24:27], v[158:161], v[224:227], v[24:27]
	v_mfma_f32_16x16x32_bf16 v[36:39], v[132:135], v[232:235], v[36:39]
	v_mfma_f32_16x16x32_bf16 v[100:103], v[158:161], v[232:235], v[100:103]
	s_setprio 0
	s_setprio 1
	v_mfma_f32_16x16x32_bf16 v[44:47], v[168:171], v[204:207], v[44:47]
	v_mfma_f32_16x16x32_bf16 v[40:43], v[196:199], v[204:207], v[40:43]
	v_mfma_f32_16x16x32_bf16 v[0:3], v[168:171], v[212:215], v[0:3]
	v_mfma_f32_16x16x32_bf16 v[4:7], v[196:199], v[212:215], v[4:7]
	v_mfma_f32_16x16x32_bf16 v[12:15], v[168:171], v[220:223], v[12:15]
	v_mfma_f32_16x16x32_bf16 v[20:23], v[196:199], v[220:223], v[20:23]
	v_mfma_f32_16x16x32_bf16 v[92:95], v[168:171], v[228:231], v[92:95]
	v_mfma_f32_16x16x32_bf16 v[32:35], v[196:199], v[228:231], v[32:35]
	v_mfma_f32_16x16x32_bf16 v[44:47], v[172:175], v[208:211], v[44:47]
	v_mfma_f32_16x16x32_bf16 v[40:43], v[200:203], v[208:211], v[40:43]
	v_mfma_f32_16x16x32_bf16 v[0:3], v[172:175], v[216:219], v[0:3]
	v_mfma_f32_16x16x32_bf16 v[4:7], v[200:203], v[216:219], v[4:7]
	v_mfma_f32_16x16x32_bf16 v[12:15], v[172:175], v[224:227], v[12:15]
	v_mfma_f32_16x16x32_bf16 v[20:23], v[200:203], v[224:227], v[20:23]
	v_mfma_f32_16x16x32_bf16 v[92:95], v[172:175], v[232:235], v[92:95]
	v_mfma_f32_16x16x32_bf16 v[32:35], v[200:203], v[232:235], v[32:35]
	s_barrier
	s_setprio 0
	s_add_i32 s87, 0, 0x18000
	s_add_i32 s88, 0, 0x1c000
	v_add_u32_e32 v158, s87, v167
	v_add_u32_e32 v164, s88, v167
	ds_read_b128 v[128:131], v158
	ds_read_b128 v[132:135], v158 offset:1024
	ds_read_b128 v[136:139], v158 offset:2048
	ds_read_b128 v[158:161], v158 offset:3072
	ds_read_b128 v[168:171], v164
	ds_read_b128 v[172:175], v164 offset:1024
	ds_read_b128 v[196:199], v164 offset:2048
	ds_read_b128 v[200:203], v164 offset:3072
	s_add_u32 s68, s68, 0x40000
	s_addc_u32 s69, s69, 0
	s_mov_b32 m0, s72
	v_lshl_add_u64 v[238:239], s[68:69], 0, v[140:141]
	ds_read_b128 v[204:207], v194 offset:32768
	ds_read_b128 v[208:211], v194 offset:33792
	ds_read_b128 v[212:215], v194 offset:34816
	ds_read_b128 v[216:219], v194 offset:35840
	ds_read_b128 v[220:223], v194 offset:36864
	ds_read_b128 v[224:227], v194 offset:37888
	ds_read_b128 v[228:231], v194 offset:38912
	ds_read_b128 v[232:235], v194 offset:39936
	global_load_lds_dwordx4 v[238:239], off
	v_lshl_add_u64 v[238:239], s[68:69], 0, v[142:143]
	s_mov_b32 m0, s73
	s_nop 0
	global_load_lds_dwordx4 v[238:239], off
	s_waitcnt vmcnt(8)
	s_waitcnt lgkmcnt(0)
	s_setprio 1
	s_barrier
	v_mfma_f32_16x16x32_bf16 v[124:127], v[128:131], v[204:207], v[124:127]
	v_mfma_f32_16x16x32_bf16 v[120:123], v[136:139], v[204:207], v[120:123]
	v_mfma_f32_16x16x32_bf16 v[96:99], v[128:131], v[212:215], v[96:99]
	v_mfma_f32_16x16x32_bf16 v[88:91], v[136:139], v[212:215], v[88:91]
	v_mfma_f32_16x16x32_bf16 v[76:79], v[128:131], v[220:223], v[76:79]
	v_mfma_f32_16x16x32_bf16 v[72:75], v[136:139], v[220:223], v[72:75]
	v_mfma_f32_16x16x32_bf16 v[60:63], v[128:131], v[228:231], v[60:63]
	v_mfma_f32_16x16x32_bf16 v[108:111], v[136:139], v[228:231], v[108:111]
	v_mfma_f32_16x16x32_bf16 v[124:127], v[132:135], v[208:211], v[124:127]
	v_mfma_f32_16x16x32_bf16 v[120:123], v[158:161], v[208:211], v[120:123]
	v_mfma_f32_16x16x32_bf16 v[96:99], v[132:135], v[216:219], v[96:99]
	v_mfma_f32_16x16x32_bf16 v[88:91], v[158:161], v[216:219], v[88:91]
	v_mfma_f32_16x16x32_bf16 v[76:79], v[132:135], v[224:227], v[76:79]
	v_mfma_f32_16x16x32_bf16 v[72:75], v[158:161], v[224:227], v[72:75]
	v_mfma_f32_16x16x32_bf16 v[60:63], v[132:135], v[232:235], v[60:63]
	v_mfma_f32_16x16x32_bf16 v[108:111], v[158:161], v[232:235], v[108:111]
	s_setprio 0
	s_setprio 1
	v_mfma_f32_16x16x32_bf16 v[116:119], v[168:171], v[204:207], v[116:119]
	v_mfma_f32_16x16x32_bf16 v[112:115], v[196:199], v[204:207], v[112:115]
	v_mfma_f32_16x16x32_bf16 v[84:87], v[168:171], v[212:215], v[84:87]
	v_mfma_f32_16x16x32_bf16 v[80:83], v[196:199], v[212:215], v[80:83]
	v_mfma_f32_16x16x32_bf16 v[68:71], v[168:171], v[220:223], v[68:71]
	v_mfma_f32_16x16x32_bf16 v[64:67], v[196:199], v[220:223], v[64:67]
	v_mfma_f32_16x16x32_bf16 v[104:107], v[168:171], v[228:231], v[104:107]
	v_mfma_f32_16x16x32_bf16 v[56:59], v[196:199], v[228:231], v[56:59]
	v_mfma_f32_16x16x32_bf16 v[116:119], v[172:175], v[208:211], v[116:119]
	v_mfma_f32_16x16x32_bf16 v[112:115], v[200:203], v[208:211], v[112:115]
	v_mfma_f32_16x16x32_bf16 v[84:87], v[172:175], v[216:219], v[84:87]
	v_mfma_f32_16x16x32_bf16 v[80:83], v[200:203], v[216:219], v[80:83]
	v_mfma_f32_16x16x32_bf16 v[68:71], v[172:175], v[224:227], v[68:71]
	v_mfma_f32_16x16x32_bf16 v[64:67], v[200:203], v[224:227], v[64:67]
	v_mfma_f32_16x16x32_bf16 v[104:107], v[172:175], v[232:235], v[104:107]
	v_mfma_f32_16x16x32_bf16 v[56:59], v[200:203], v[232:235], v[56:59]
	s_barrier
	s_setprio 0
	s_add_i32 s68, s87, s23
	v_lshl_add_u64 v[162:163], v[162:163], 0, s[36:37]
	s_mov_b32 m0, s68
	ds_read_b128 v[204:207], v194 offset:49152
	ds_read_b128 v[208:211], v194 offset:50176
	ds_read_b128 v[212:215], v194 offset:51200
	ds_read_b128 v[216:219], v194 offset:52224
	ds_read_b128 v[220:223], v194 offset:53248
	ds_read_b128 v[224:227], v194 offset:54272
	ds_read_b128 v[228:231], v194 offset:55296
	ds_read_b128 v[232:235], v194 offset:56320
	global_load_lds_dwordx4 v[162:163], off
	s_add_i32 m0, s68, 0x2000
	s_add_u32 s66, s66, 0x40080
	v_lshl_add_u64 v[162:163], v[178:179], 0, s[36:37]
	s_addc_u32 s67, s67, 0
	s_add_i32 s68, s88, s23
	global_load_lds_dwordx4 v[162:163], off
	v_lshl_add_u64 v[162:163], s[66:67], 0, v[140:141]
	s_mov_b32 m0, s68
	s_nop 0
	global_load_lds_dwordx4 v[162:163], off
	v_lshl_add_u64 v[162:163], s[66:67], 0, v[142:143]
	s_add_i32 m0, s68, 0x2000
	s_nop 0
	global_load_lds_dwordx4 v[162:163], off
	v_lshl_add_u64 v[162:163], v[184:185], 0, s[36:37]
	s_mov_b32 m0, s80
	s_nop 0
	global_load_lds_dwordx4 v[162:163], off
	v_lshl_add_u64 v[162:163], v[236:237], 0, s[36:37]
	s_mov_b32 m0, s81
	s_nop 0
	global_load_lds_dwordx4 v[162:163], off
	s_waitcnt vmcnt(8)
	s_waitcnt lgkmcnt(0)
	s_setprio 1
	s_barrier
	v_mfma_f32_16x16x32_bf16 v[52:55], v[128:131], v[204:207], v[52:55]
	v_mfma_f32_16x16x32_bf16 v[48:51], v[136:139], v[204:207], v[48:51]
	v_mfma_f32_16x16x32_bf16 v[16:19], v[128:131], v[212:215], v[16:19]
	v_mfma_f32_16x16x32_bf16 v[8:11], v[136:139], v[212:215], v[8:11]
	v_mfma_f32_16x16x32_bf16 v[28:31], v[128:131], v[220:223], v[28:31]
	v_mfma_f32_16x16x32_bf16 v[24:27], v[136:139], v[220:223], v[24:27]
	v_mfma_f32_16x16x32_bf16 v[36:39], v[128:131], v[228:231], v[36:39]
	v_mfma_f32_16x16x32_bf16 v[100:103], v[136:139], v[228:231], v[100:103]
	v_mfma_f32_16x16x32_bf16 v[52:55], v[132:135], v[208:211], v[52:55]
	v_mfma_f32_16x16x32_bf16 v[48:51], v[158:161], v[208:211], v[48:51]
	v_mfma_f32_16x16x32_bf16 v[16:19], v[132:135], v[216:219], v[16:19]
	v_mfma_f32_16x16x32_bf16 v[8:11], v[158:161], v[216:219], v[8:11]
	v_mfma_f32_16x16x32_bf16 v[28:31], v[132:135], v[224:227], v[28:31]
	v_mfma_f32_16x16x32_bf16 v[24:27], v[158:161], v[224:227], v[24:27]
	v_mfma_f32_16x16x32_bf16 v[36:39], v[132:135], v[232:235], v[36:39]
	v_mfma_f32_16x16x32_bf16 v[100:103], v[158:161], v[232:235], v[100:103]
	s_setprio 0
	s_setprio 1
	v_mfma_f32_16x16x32_bf16 v[44:47], v[168:171], v[204:207], v[44:47]
	v_mfma_f32_16x16x32_bf16 v[40:43], v[196:199], v[204:207], v[40:43]
	v_mfma_f32_16x16x32_bf16 v[0:3], v[168:171], v[212:215], v[0:3]
	v_mfma_f32_16x16x32_bf16 v[4:7], v[196:199], v[212:215], v[4:7]
	v_mfma_f32_16x16x32_bf16 v[12:15], v[168:171], v[220:223], v[12:15]
	v_mfma_f32_16x16x32_bf16 v[20:23], v[196:199], v[220:223], v[20:23]
	v_mfma_f32_16x16x32_bf16 v[92:95], v[168:171], v[228:231], v[92:95]
	v_mfma_f32_16x16x32_bf16 v[32:35], v[196:199], v[228:231], v[32:35]
	v_mfma_f32_16x16x32_bf16 v[44:47], v[172:175], v[208:211], v[44:47]
	v_mfma_f32_16x16x32_bf16 v[40:43], v[200:203], v[208:211], v[40:43]
	v_mfma_f32_16x16x32_bf16 v[0:3], v[172:175], v[216:219], v[0:3]
	v_mfma_f32_16x16x32_bf16 v[4:7], v[200:203], v[216:219], v[4:7]
	v_mfma_f32_16x16x32_bf16 v[12:15], v[172:175], v[224:227], v[12:15]
	v_mfma_f32_16x16x32_bf16 v[20:23], v[200:203], v[224:227], v[20:23]
	v_mfma_f32_16x16x32_bf16 v[92:95], v[172:175], v[232:235], v[92:95]
	v_mfma_f32_16x16x32_bf16 v[32:35], v[200:203], v[232:235], v[32:35]
	s_barrier
	s_setprio 0
	s_add_i32 s86, s86, 2
	s_add_u32 s64, s64, 0x100
	s_addc_u32 s65, s65, 0
	s_add_u32 s84, s84, 0x100
	s_addc_u32 s85, s85, 0
	s_cmp_gt_u32 s86, 13
	s_cbranch_scc0 .LBB0_439
	s_and_b64 vcc, exec, s[38:39]
	s_cbranch_vccz .LBB0_442
	s_barrier

.LBB0_504:
	ds_read_b128 v[104:107], v200
	ds_read_b128 v[108:111], v200 offset:1024
	ds_read_b128 v[124:127], v200 offset:2048
	ds_read_b128 v[128:131], v200 offset:3072
	ds_read_b128 v[144:147], v201
	ds_read_b128 v[148:151], v201 offset:1024
	ds_read_b128 v[152:155], v201 offset:2048
	ds_read_b128 v[156:159], v201 offset:3072
	s_add_u32 s48, s46, 0xfffc0080
	s_addc_u32 s49, s47, -1
	s_cmp_eq_u32 s87, 12
	s_cselect_b32 s51, s39, s49
	s_cselect_b32 s50, s45, s48
	s_cselect_b32 s49, s37, s86
	s_cselect_b32 s48, s84, s85
	v_lshl_add_u64 v[196:197], s[46:47], 0, v[188:189]
	s_add_i32 m0, s52, 0xc000
	ds_read_b128 v[160:163], v202
	ds_read_b128 v[164:167], v202 offset:1024
	ds_read_b128 v[168:171], v202 offset:2048
	ds_read_b128 v[172:175], v202 offset:3072
	ds_read_b128 v[176:179], v202 offset:4096
	ds_read_b128 v[180:183], v202 offset:5120
	ds_read_b128 v[206:209], v202 offset:6144
	ds_read_b128 v[210:213], v202 offset:7168
	global_load_lds_dwordx4 v[196:197], off
	v_lshl_add_u64 v[196:197], s[46:47], 0, v[190:191]
	s_add_i32 m0, s52, 0xe000
	s_nop 0
	global_load_lds_dwordx4 v[196:197], off
	s_waitcnt vmcnt(8)
	s_waitcnt lgkmcnt(0)
	s_setprio 1
	s_barrier
	v_mfma_f32_16x16x32_bf16 v[140:143], v[104:107], v[160:163], v[140:143]
	v_mfma_f32_16x16x32_bf16 v[136:139], v[124:127], v[160:163], v[136:139]
	v_mfma_f32_16x16x32_bf16 v[116:119], v[104:107], v[168:171], v[116:119]
	v_mfma_f32_16x16x32_bf16 v[112:115], v[124:127], v[168:171], v[112:115]
	v_mfma_f32_16x16x32_bf16 v[92:95], v[104:107], v[176:179], v[92:95]
	v_mfma_f32_16x16x32_bf16 v[88:91], v[124:127], v[176:179], v[88:91]
	v_mfma_f32_16x16x32_bf16 v[76:79], v[104:107], v[206:209], v[76:79]
	v_mfma_f32_16x16x32_bf16 v[72:75], v[124:127], v[206:209], v[72:75]
	v_mfma_f32_16x16x32_bf16 v[140:143], v[108:111], v[164:167], v[140:143]
	v_mfma_f32_16x16x32_bf16 v[136:139], v[128:131], v[164:167], v[136:139]
	v_mfma_f32_16x16x32_bf16 v[116:119], v[108:111], v[172:175], v[116:119]
	v_mfma_f32_16x16x32_bf16 v[112:115], v[128:131], v[172:175], v[112:115]
	v_mfma_f32_16x16x32_bf16 v[92:95], v[108:111], v[180:183], v[92:95]
	v_mfma_f32_16x16x32_bf16 v[88:91], v[128:131], v[180:183], v[88:91]
	v_mfma_f32_16x16x32_bf16 v[76:79], v[108:111], v[210:213], v[76:79]
	v_mfma_f32_16x16x32_bf16 v[72:75], v[128:131], v[210:213], v[72:75]
	s_setprio 0
	s_setprio 1
	v_mfma_f32_16x16x32_bf16 v[132:135], v[144:147], v[160:163], v[132:135]
	v_mfma_f32_16x16x32_bf16 v[120:123], v[152:155], v[160:163], v[120:123]
	v_mfma_f32_16x16x32_bf16 v[100:103], v[144:147], v[168:171], v[100:103]
	v_mfma_f32_16x16x32_bf16 v[96:99], v[152:155], v[168:171], v[96:99]
	v_mfma_f32_16x16x32_bf16 v[84:87], v[144:147], v[176:179], v[84:87]
	v_mfma_f32_16x16x32_bf16 v[80:83], v[152:155], v[176:179], v[80:83]
	v_mfma_f32_16x16x32_bf16 v[68:71], v[144:147], v[206:209], v[68:71]
	v_mfma_f32_16x16x32_bf16 v[64:67], v[152:155], v[206:209], v[64:67]
	v_mfma_f32_16x16x32_bf16 v[132:135], v[148:151], v[164:167], v[132:135]
	v_mfma_f32_16x16x32_bf16 v[120:123], v[156:159], v[164:167], v[120:123]
	v_mfma_f32_16x16x32_bf16 v[100:103], v[148:151], v[172:175], v[100:103]
	v_mfma_f32_16x16x32_bf16 v[96:99], v[156:159], v[172:175], v[96:99]
	v_mfma_f32_16x16x32_bf16 v[84:87], v[148:151], v[180:183], v[84:87]
	v_mfma_f32_16x16x32_bf16 v[80:83], v[156:159], v[180:183], v[80:83]
	v_mfma_f32_16x16x32_bf16 v[68:71], v[148:151], v[210:213], v[68:71]
	v_mfma_f32_16x16x32_bf16 v[64:67], v[156:159], v[210:213], v[64:67]
	s_barrier
	s_setprio 0
	s_add_i32 s88, s69, s13
	v_lshl_add_u64 v[196:197], s[48:49], 0, v[184:185]
	s_mov_b32 m0, s88
	ds_read_b128 v[160:163], v202 offset:16384
	ds_read_b128 v[164:167], v202 offset:17408
	ds_read_b128 v[168:171], v202 offset:18432
	ds_read_b128 v[172:175], v202 offset:19456
	ds_read_b128 v[176:179], v202 offset:20480
	ds_read_b128 v[180:183], v202 offset:21504
	ds_read_b128 v[206:209], v202 offset:22528
	ds_read_b128 v[210:213], v202 offset:23552
	global_load_lds_dwordx4 v[196:197], off
	s_add_i32 m0, s88, 0x2000
	s_add_u32 s88, s48, 0x40000
	v_lshl_add_u64 v[214:215], s[48:49], 0, v[186:187]
	s_addc_u32 s89, s49, 0
	s_add_i32 s90, s70, s13
	global_load_lds_dwordx4 v[214:215], off
	v_lshl_add_u64 v[216:217], s[88:89], 0, v[184:185]
	s_mov_b32 m0, s90
	v_lshl_add_u64 v[218:219], s[50:51], 0, v[186:187]
	global_load_lds_dwordx4 v[216:217], off
	v_lshl_add_u64 v[216:217], s[88:89], 0, v[186:187]
	s_add_i32 m0, s90, 0x2000
	s_nop 0
	global_load_lds_dwordx4 v[216:217], off
	v_lshl_add_u64 v[216:217], s[50:51], 0, v[184:185]
	s_mov_b32 m0, s52
	s_nop 0
	global_load_lds_dwordx4 v[216:217], off
	s_mov_b32 m0, s53
	s_nop 0
	global_load_lds_dwordx4 v[218:219], off
	s_waitcnt vmcnt(8)
	s_waitcnt lgkmcnt(0)
	s_setprio 1
	s_barrier
	v_mfma_f32_16x16x32_bf16 v[60:63], v[104:107], v[160:163], v[60:63]
	v_mfma_f32_16x16x32_bf16 v[56:59], v[124:127], v[160:163], v[56:59]
	v_mfma_f32_16x16x32_bf16 v[44:47], v[104:107], v[168:171], v[44:47]
	v_mfma_f32_16x16x32_bf16 v[40:43], v[124:127], v[168:171], v[40:43]
	v_mfma_f32_16x16x32_bf16 v[28:31], v[104:107], v[176:179], v[28:31]
	v_mfma_f32_16x16x32_bf16 v[24:27], v[124:127], v[176:179], v[24:27]
	v_mfma_f32_16x16x32_bf16 v[12:15], v[104:107], v[206:209], v[12:15]
	v_mfma_f32_16x16x32_bf16 v[8:11], v[124:127], v[206:209], v[8:11]
	v_mfma_f32_16x16x32_bf16 v[60:63], v[108:111], v[164:167], v[60:63]
	v_mfma_f32_16x16x32_bf16 v[56:59], v[128:131], v[164:167], v[56:59]
	v_mfma_f32_16x16x32_bf16 v[44:47], v[108:111], v[172:175], v[44:47]
	v_mfma_f32_16x16x32_bf16 v[40:43], v[128:131], v[172:175], v[40:43]
	v_mfma_f32_16x16x32_bf16 v[28:31], v[108:111], v[180:183], v[28:31]
	v_mfma_f32_16x16x32_bf16 v[24:27], v[128:131], v[180:183], v[24:27]
	v_mfma_f32_16x16x32_bf16 v[12:15], v[108:111], v[210:213], v[12:15]
	v_mfma_f32_16x16x32_bf16 v[8:11], v[128:131], v[210:213], v[8:11]
	s_setprio 0
	s_setprio 1
	v_mfma_f32_16x16x32_bf16 v[52:55], v[144:147], v[160:163], v[52:55]
	v_mfma_f32_16x16x32_bf16 v[48:51], v[152:155], v[160:163], v[48:51]
	v_mfma_f32_16x16x32_bf16 v[36:39], v[144:147], v[168:171], v[36:39]
	v_mfma_f32_16x16x32_bf16 v[32:35], v[152:155], v[168:171], v[32:35]
	v_mfma_f32_16x16x32_bf16 v[20:23], v[144:147], v[176:179], v[20:23]
	v_mfma_f32_16x16x32_bf16 v[16:19], v[152:155], v[176:179], v[16:19]
	v_mfma_f32_16x16x32_bf16 v[4:7], v[144:147], v[206:209], v[4:7]
	v_mfma_f32_16x16x32_bf16 v[0:3], v[152:155], v[206:209], v[0:3]
	v_mfma_f32_16x16x32_bf16 v[52:55], v[148:151], v[164:167], v[52:55]
	v_mfma_f32_16x16x32_bf16 v[48:51], v[156:159], v[164:167], v[48:51]
	v_mfma_f32_16x16x32_bf16 v[36:39], v[148:151], v[172:175], v[36:39]
	v_mfma_f32_16x16x32_bf16 v[32:35], v[156:159], v[172:175], v[32:35]
	v_mfma_f32_16x16x32_bf16 v[20:23], v[148:151], v[180:183], v[20:23]
	v_mfma_f32_16x16x32_bf16 v[16:19], v[156:159], v[180:183], v[16:19]
	v_mfma_f32_16x16x32_bf16 v[4:7], v[148:151], v[210:213], v[4:7]
	v_mfma_f32_16x16x32_bf16 v[0:3], v[156:159], v[210:213], v[0:3]
	s_barrier
	s_setprio 0
	s_add_i32 s88, 0, 0x18000
	s_add_i32 s89, 0, 0x1c000
	v_add_u32_e32 v128, s88, v199
	v_add_u32_e32 v156, s89, v199
	ds_read_b128 v[104:107], v128
	ds_read_b128 v[108:111], v128 offset:1024
	ds_read_b128 v[124:127], v128 offset:2048
	ds_read_b128 v[128:131], v128 offset:3072
	ds_read_b128 v[144:147], v156
	ds_read_b128 v[148:151], v156 offset:1024
	ds_read_b128 v[152:155], v156 offset:2048
	ds_read_b128 v[156:159], v156 offset:3072
	s_add_u32 s50, s50, 0x40000
	s_addc_u32 s51, s51, 0
	s_mov_b32 m0, s54
	v_lshl_add_u64 v[220:221], s[50:51], 0, v[184:185]
	ds_read_b128 v[160:163], v202 offset:32768
	ds_read_b128 v[164:167], v202 offset:33792
	ds_read_b128 v[168:171], v202 offset:34816
	ds_read_b128 v[172:175], v202 offset:35840
	ds_read_b128 v[176:179], v202 offset:36864
	ds_read_b128 v[180:183], v202 offset:37888
	ds_read_b128 v[206:209], v202 offset:38912
	ds_read_b128 v[210:213], v202 offset:39936
	global_load_lds_dwordx4 v[220:221], off
	v_lshl_add_u64 v[220:221], s[50:51], 0, v[186:187]
	s_mov_b32 m0, s55
	s_nop 0
	global_load_lds_dwordx4 v[220:221], off
	s_waitcnt vmcnt(8)
	s_waitcnt lgkmcnt(0)
	s_setprio 1
	s_barrier
	v_mfma_f32_16x16x32_bf16 v[140:143], v[104:107], v[160:163], v[140:143]
	v_mfma_f32_16x16x32_bf16 v[136:139], v[124:127], v[160:163], v[136:139]
	v_mfma_f32_16x16x32_bf16 v[116:119], v[104:107], v[168:171], v[116:119]
	v_mfma_f32_16x16x32_bf16 v[112:115], v[124:127], v[168:171], v[112:115]
	v_mfma_f32_16x16x32_bf16 v[92:95], v[104:107], v[176:179], v[92:95]
	v_mfma_f32_16x16x32_bf16 v[88:91], v[124:127], v[176:179], v[88:91]
	v_mfma_f32_16x16x32_bf16 v[76:79], v[104:107], v[206:209], v[76:79]
	v_mfma_f32_16x16x32_bf16 v[72:75], v[124:127], v[206:209], v[72:75]
	v_mfma_f32_16x16x32_bf16 v[140:143], v[108:111], v[164:167], v[140:143]
	v_mfma_f32_16x16x32_bf16 v[136:139], v[128:131], v[164:167], v[136:139]
	v_mfma_f32_16x16x32_bf16 v[116:119], v[108:111], v[172:175], v[116:119]
	v_mfma_f32_16x16x32_bf16 v[112:115], v[128:131], v[172:175], v[112:115]
	v_mfma_f32_16x16x32_bf16 v[92:95], v[108:111], v[180:183], v[92:95]
	v_mfma_f32_16x16x32_bf16 v[88:91], v[128:131], v[180:183], v[88:91]
	v_mfma_f32_16x16x32_bf16 v[76:79], v[108:111], v[210:213], v[76:79]
	v_mfma_f32_16x16x32_bf16 v[72:75], v[128:131], v[210:213], v[72:75]
	s_setprio 0
	s_setprio 1
	v_mfma_f32_16x16x32_bf16 v[132:135], v[144:147], v[160:163], v[132:135]
	v_mfma_f32_16x16x32_bf16 v[120:123], v[152:155], v[160:163], v[120:123]
	v_mfma_f32_16x16x32_bf16 v[100:103], v[144:147], v[168:171], v[100:103]
	v_mfma_f32_16x16x32_bf16 v[96:99], v[152:155], v[168:171], v[96:99]
	v_mfma_f32_16x16x32_bf16 v[84:87], v[144:147], v[176:179], v[84:87]
	v_mfma_f32_16x16x32_bf16 v[80:83], v[152:155], v[176:179], v[80:83]
	v_mfma_f32_16x16x32_bf16 v[68:71], v[144:147], v[206:209], v[68:71]
	v_mfma_f32_16x16x32_bf16 v[64:67], v[152:155], v[206:209], v[64:67]
	v_mfma_f32_16x16x32_bf16 v[132:135], v[148:151], v[164:167], v[132:135]
	v_mfma_f32_16x16x32_bf16 v[120:123], v[156:159], v[164:167], v[120:123]
	v_mfma_f32_16x16x32_bf16 v[100:103], v[148:151], v[172:175], v[100:103]
	v_mfma_f32_16x16x32_bf16 v[96:99], v[156:159], v[172:175], v[96:99]
	v_mfma_f32_16x16x32_bf16 v[84:87], v[148:151], v[180:183], v[84:87]
	v_mfma_f32_16x16x32_bf16 v[80:83], v[156:159], v[180:183], v[80:83]
	v_mfma_f32_16x16x32_bf16 v[68:71], v[148:151], v[210:213], v[68:71]
	v_mfma_f32_16x16x32_bf16 v[64:67], v[156:159], v[210:213], v[64:67]
	s_barrier
	s_setprio 0
	s_add_i32 s50, s88, s13
	v_lshl_add_u64 v[196:197], v[196:197], 0, s[30:31]
	s_mov_b32 m0, s50
	ds_read_b128 v[160:163], v202 offset:49152
	ds_read_b128 v[164:167], v202 offset:50176
	ds_read_b128 v[168:171], v202 offset:51200
	ds_read_b128 v[172:175], v202 offset:52224
	ds_read_b128 v[176:179], v202 offset:53248
	ds_read_b128 v[180:183], v202 offset:54272
	ds_read_b128 v[206:209], v202 offset:55296
	ds_read_b128 v[210:213], v202 offset:56320
	global_load_lds_dwordx4 v[196:197], off
	s_add_i32 m0, s50, 0x2000
	s_add_u32 s48, s48, 0x40080
	v_lshl_add_u64 v[196:197], v[214:215], 0, s[30:31]
	s_addc_u32 s49, s49, 0
	s_add_i32 s50, s89, s13
	global_load_lds_dwordx4 v[196:197], off
	v_lshl_add_u64 v[196:197], s[48:49], 0, v[184:185]
	s_mov_b32 m0, s50
	s_nop 0
	global_load_lds_dwordx4 v[196:197], off
	v_lshl_add_u64 v[196:197], s[48:49], 0, v[186:187]
	s_add_i32 m0, s50, 0x2000
	s_nop 0
	global_load_lds_dwordx4 v[196:197], off
	v_lshl_add_u64 v[196:197], v[216:217], 0, s[30:31]
	s_mov_b32 m0, s61
	s_nop 0
	global_load_lds_dwordx4 v[196:197], off
	v_lshl_add_u64 v[196:197], v[218:219], 0, s[30:31]
	s_mov_b32 m0, s62
	s_nop 0
	global_load_lds_dwordx4 v[196:197], off
	s_waitcnt vmcnt(8)
	s_waitcnt lgkmcnt(0)
	s_setprio 1
	s_barrier
	v_mfma_f32_16x16x32_bf16 v[60:63], v[104:107], v[160:163], v[60:63]
	v_mfma_f32_16x16x32_bf16 v[56:59], v[124:127], v[160:163], v[56:59]
	v_mfma_f32_16x16x32_bf16 v[44:47], v[104:107], v[168:171], v[44:47]
	v_mfma_f32_16x16x32_bf16 v[40:43], v[124:127], v[168:171], v[40:43]
	v_mfma_f32_16x16x32_bf16 v[28:31], v[104:107], v[176:179], v[28:31]
	v_mfma_f32_16x16x32_bf16 v[24:27], v[124:127], v[176:179], v[24:27]
	v_mfma_f32_16x16x32_bf16 v[12:15], v[104:107], v[206:209], v[12:15]
	v_mfma_f32_16x16x32_bf16 v[8:11], v[124:127], v[206:209], v[8:11]
	v_mfma_f32_16x16x32_bf16 v[60:63], v[108:111], v[164:167], v[60:63]
	v_mfma_f32_16x16x32_bf16 v[56:59], v[128:131], v[164:167], v[56:59]
	v_mfma_f32_16x16x32_bf16 v[44:47], v[108:111], v[172:175], v[44:47]
	v_mfma_f32_16x16x32_bf16 v[40:43], v[128:131], v[172:175], v[40:43]
	v_mfma_f32_16x16x32_bf16 v[28:31], v[108:111], v[180:183], v[28:31]
	v_mfma_f32_16x16x32_bf16 v[24:27], v[128:131], v[180:183], v[24:27]
	v_mfma_f32_16x16x32_bf16 v[12:15], v[108:111], v[210:213], v[12:15]
	v_mfma_f32_16x16x32_bf16 v[8:11], v[128:131], v[210:213], v[8:11]
	s_setprio 0
	s_setprio 1
	v_mfma_f32_16x16x32_bf16 v[52:55], v[144:147], v[160:163], v[52:55]
	v_mfma_f32_16x16x32_bf16 v[48:51], v[152:155], v[160:163], v[48:51]
	v_mfma_f32_16x16x32_bf16 v[36:39], v[144:147], v[168:171], v[36:39]
	v_mfma_f32_16x16x32_bf16 v[32:35], v[152:155], v[168:171], v[32:35]
	v_mfma_f32_16x16x32_bf16 v[20:23], v[144:147], v[176:179], v[20:23]
	v_mfma_f32_16x16x32_bf16 v[16:19], v[152:155], v[176:179], v[16:19]
	v_mfma_f32_16x16x32_bf16 v[4:7], v[144:147], v[206:209], v[4:7]
	v_mfma_f32_16x16x32_bf16 v[0:3], v[152:155], v[206:209], v[0:3]
	v_mfma_f32_16x16x32_bf16 v[52:55], v[148:151], v[164:167], v[52:55]
	v_mfma_f32_16x16x32_bf16 v[48:51], v[156:159], v[164:167], v[48:51]
	v_mfma_f32_16x16x32_bf16 v[36:39], v[148:151], v[172:175], v[36:39]
	v_mfma_f32_16x16x32_bf16 v[32:35], v[156:159], v[172:175], v[32:35]
	v_mfma_f32_16x16x32_bf16 v[20:23], v[148:151], v[180:183], v[20:23]
	v_mfma_f32_16x16x32_bf16 v[16:19], v[156:159], v[180:183], v[16:19]
	v_mfma_f32_16x16x32_bf16 v[4:7], v[148:151], v[210:213], v[4:7]
	v_mfma_f32_16x16x32_bf16 v[0:3], v[156:159], v[210:213], v[0:3]
	s_barrier
	s_setprio 0
	s_add_i32 s87, s87, 2
	s_add_u32 s46, s46, 0x100
	s_addc_u32 s47, s47, 0
	s_add_u32 s85, s85, 0x100
	s_addc_u32 s86, s86, 0
	s_cmp_gt_u32 s87, 13
	s_cbranch_scc0 .LBB0_504
	s_and_b64 vcc, exec, s[34:35]
	s_cbranch_vccz .LBB0_507
	s_barrier

.LBB0_552:
	ds_read_b128 v[128:131], v173
	ds_read_b128 v[132:135], v173 offset:1024
	ds_read_b128 v[136:139], v173 offset:2048
	ds_read_b128 v[140:143], v173 offset:3072
	ds_read_b128 v[160:163], v179
	ds_read_b128 v[174:177], v179 offset:1024
	ds_read_b128 v[194:197], v179 offset:2048
	ds_read_b128 v[198:201], v179 offset:3072
	s_add_u32 s57, s62, 0xfffc0080
	s_addc_u32 s64, s63, -1
	s_cmp_eq_u32 s55, 12
	s_cselect_b32 s67, s9, s64
	s_cselect_b32 s66, s11, s57
	s_cselect_b32 s65, s13, s23
	s_cselect_b32 s64, s16, s22
	v_lshl_add_u64 v[166:167], s[62:63], 0, v[152:153]
	s_add_i32 m0, s86, 0xc000
	ds_read_b128 v[202:205], v183
	ds_read_b128 v[206:209], v183 offset:1024
	ds_read_b128 v[210:213], v183 offset:2048
	ds_read_b128 v[214:217], v183 offset:3072
	ds_read_b128 v[218:221], v183 offset:4096
	ds_read_b128 v[222:225], v183 offset:5120
	ds_read_b128 v[226:229], v183 offset:6144
	ds_read_b128 v[230:233], v183 offset:7168
	global_load_lds_dwordx4 v[166:167], off
	v_lshl_add_u64 v[166:167], s[62:63], 0, v[154:155]
	s_add_i32 m0, s86, 0xe000
	s_nop 0
	global_load_lds_dwordx4 v[166:167], off
	s_waitcnt vmcnt(8)
	s_waitcnt lgkmcnt(0)
	s_setprio 1
	s_barrier
	v_mfma_f32_16x16x32_bf16 v[124:127], v[128:131], v[202:205], v[124:127]
	v_mfma_f32_16x16x32_bf16 v[120:123], v[136:139], v[202:205], v[120:123]
	v_mfma_f32_16x16x32_bf16 v[108:111], v[128:131], v[210:213], v[108:111]
	v_mfma_f32_16x16x32_bf16 v[104:107], v[136:139], v[210:213], v[104:107]
	v_mfma_f32_16x16x32_bf16 v[92:95], v[128:131], v[218:221], v[92:95]
	v_mfma_f32_16x16x32_bf16 v[88:91], v[136:139], v[218:221], v[88:91]
	v_mfma_f32_16x16x32_bf16 v[76:79], v[128:131], v[226:229], v[76:79]
	v_mfma_f32_16x16x32_bf16 v[72:75], v[136:139], v[226:229], v[72:75]
	v_mfma_f32_16x16x32_bf16 v[124:127], v[132:135], v[206:209], v[124:127]
	v_mfma_f32_16x16x32_bf16 v[120:123], v[140:143], v[206:209], v[120:123]
	v_mfma_f32_16x16x32_bf16 v[108:111], v[132:135], v[214:217], v[108:111]
	v_mfma_f32_16x16x32_bf16 v[104:107], v[140:143], v[214:217], v[104:107]
	v_mfma_f32_16x16x32_bf16 v[92:95], v[132:135], v[222:225], v[92:95]
	v_mfma_f32_16x16x32_bf16 v[88:91], v[140:143], v[222:225], v[88:91]
	v_mfma_f32_16x16x32_bf16 v[76:79], v[132:135], v[230:233], v[76:79]
	v_mfma_f32_16x16x32_bf16 v[72:75], v[140:143], v[230:233], v[72:75]
	s_setprio 0
	s_setprio 1
	v_mfma_f32_16x16x32_bf16 v[116:119], v[160:163], v[202:205], v[116:119]
	v_mfma_f32_16x16x32_bf16 v[112:115], v[194:197], v[202:205], v[112:115]
	v_mfma_f32_16x16x32_bf16 v[100:103], v[160:163], v[210:213], v[100:103]
	v_mfma_f32_16x16x32_bf16 v[96:99], v[194:197], v[210:213], v[96:99]
	v_mfma_f32_16x16x32_bf16 v[84:87], v[160:163], v[218:221], v[84:87]
	v_mfma_f32_16x16x32_bf16 v[80:83], v[194:197], v[218:221], v[80:83]
	v_mfma_f32_16x16x32_bf16 v[68:71], v[160:163], v[226:229], v[68:71]
	v_mfma_f32_16x16x32_bf16 v[64:67], v[194:197], v[226:229], v[64:67]
	v_mfma_f32_16x16x32_bf16 v[116:119], v[174:177], v[206:209], v[116:119]
	v_mfma_f32_16x16x32_bf16 v[112:115], v[198:201], v[206:209], v[112:115]
	v_mfma_f32_16x16x32_bf16 v[100:103], v[174:177], v[214:217], v[100:103]
	v_mfma_f32_16x16x32_bf16 v[96:99], v[198:201], v[214:217], v[96:99]
	v_mfma_f32_16x16x32_bf16 v[84:87], v[174:177], v[222:225], v[84:87]
	v_mfma_f32_16x16x32_bf16 v[80:83], v[198:201], v[222:225], v[80:83]
	v_mfma_f32_16x16x32_bf16 v[68:71], v[174:177], v[230:233], v[68:71]
	v_mfma_f32_16x16x32_bf16 v[64:67], v[198:201], v[230:233], v[64:67]
	s_barrier
	s_setprio 0
	s_add_i32 s57, s0, s85
	v_lshl_add_u64 v[166:167], s[64:65], 0, v[144:145]
	s_mov_b32 m0, s57
	ds_read_b128 v[202:205], v183 offset:16384
	ds_read_b128 v[206:209], v183 offset:17408
	ds_read_b128 v[210:213], v183 offset:18432
	ds_read_b128 v[214:217], v183 offset:19456
	ds_read_b128 v[218:221], v183 offset:20480
	ds_read_b128 v[222:225], v183 offset:21504
	ds_read_b128 v[226:229], v183 offset:22528
	ds_read_b128 v[230:233], v183 offset:23552
	global_load_lds_dwordx4 v[166:167], off
	s_add_i32 m0, s57, 0x2000
	s_add_u32 s68, s64, 0x40000
	v_lshl_add_u64 v[170:171], s[64:65], 0, v[146:147]
	s_addc_u32 s69, s65, 0
	s_add_i32 s57, s1, s85
	global_load_lds_dwordx4 v[170:171], off
	v_lshl_add_u64 v[180:181], s[68:69], 0, v[144:145]
	s_mov_b32 m0, s57
	v_lshl_add_u64 v[184:185], s[66:67], 0, v[146:147]
	global_load_lds_dwordx4 v[180:181], off
	v_lshl_add_u64 v[180:181], s[68:69], 0, v[146:147]
	s_add_i32 m0, s57, 0x2000
	s_nop 0
	global_load_lds_dwordx4 v[180:181], off
	v_lshl_add_u64 v[180:181], s[66:67], 0, v[144:145]
	s_mov_b32 m0, s86
	s_nop 0
	global_load_lds_dwordx4 v[180:181], off
	s_mov_b32 m0, s87
	s_nop 0
	global_load_lds_dwordx4 v[184:185], off
	s_waitcnt vmcnt(8)
	s_waitcnt lgkmcnt(0)
	s_setprio 1
	s_barrier
	v_mfma_f32_16x16x32_bf16 v[60:63], v[128:131], v[202:205], v[60:63]
	v_mfma_f32_16x16x32_bf16 v[56:59], v[136:139], v[202:205], v[56:59]
	v_mfma_f32_16x16x32_bf16 v[44:47], v[128:131], v[210:213], v[44:47]
	v_mfma_f32_16x16x32_bf16 v[40:43], v[136:139], v[210:213], v[40:43]
	v_mfma_f32_16x16x32_bf16 v[28:31], v[128:131], v[218:221], v[28:31]
	v_mfma_f32_16x16x32_bf16 v[24:27], v[136:139], v[218:221], v[24:27]
	v_mfma_f32_16x16x32_bf16 v[12:15], v[128:131], v[226:229], v[12:15]
	v_mfma_f32_16x16x32_bf16 v[8:11], v[136:139], v[226:229], v[8:11]
	v_mfma_f32_16x16x32_bf16 v[60:63], v[132:135], v[206:209], v[60:63]
	v_mfma_f32_16x16x32_bf16 v[56:59], v[140:143], v[206:209], v[56:59]
	v_mfma_f32_16x16x32_bf16 v[44:47], v[132:135], v[214:217], v[44:47]
	v_mfma_f32_16x16x32_bf16 v[40:43], v[140:143], v[214:217], v[40:43]
	v_mfma_f32_16x16x32_bf16 v[28:31], v[132:135], v[222:225], v[28:31]
	v_mfma_f32_16x16x32_bf16 v[24:27], v[140:143], v[222:225], v[24:27]
	v_mfma_f32_16x16x32_bf16 v[12:15], v[132:135], v[230:233], v[12:15]
	v_mfma_f32_16x16x32_bf16 v[8:11], v[140:143], v[230:233], v[8:11]
	s_setprio 0
	s_setprio 1
	v_mfma_f32_16x16x32_bf16 v[52:55], v[160:163], v[202:205], v[52:55]
	v_mfma_f32_16x16x32_bf16 v[48:51], v[194:197], v[202:205], v[48:51]
	v_mfma_f32_16x16x32_bf16 v[36:39], v[160:163], v[210:213], v[36:39]
	v_mfma_f32_16x16x32_bf16 v[32:35], v[194:197], v[210:213], v[32:35]
	v_mfma_f32_16x16x32_bf16 v[20:23], v[160:163], v[218:221], v[20:23]
	v_mfma_f32_16x16x32_bf16 v[16:19], v[194:197], v[218:221], v[16:19]
	v_mfma_f32_16x16x32_bf16 v[4:7], v[160:163], v[226:229], v[4:7]
	v_mfma_f32_16x16x32_bf16 v[0:3], v[194:197], v[226:229], v[0:3]
	v_mfma_f32_16x16x32_bf16 v[52:55], v[174:177], v[206:209], v[52:55]
	v_mfma_f32_16x16x32_bf16 v[48:51], v[198:201], v[206:209], v[48:51]
	v_mfma_f32_16x16x32_bf16 v[36:39], v[174:177], v[214:217], v[36:39]
	v_mfma_f32_16x16x32_bf16 v[32:35], v[198:201], v[214:217], v[32:35]
	v_mfma_f32_16x16x32_bf16 v[20:23], v[174:177], v[222:225], v[20:23]
	v_mfma_f32_16x16x32_bf16 v[16:19], v[198:201], v[222:225], v[16:19]
	v_mfma_f32_16x16x32_bf16 v[4:7], v[174:177], v[230:233], v[4:7]
	v_mfma_f32_16x16x32_bf16 v[0:3], v[198:201], v[230:233], v[0:3]
	s_barrier
	s_setprio 0
	s_add_i32 s57, 0, 0x18000
	s_add_i32 s68, 0, 0x1c000
	v_add_u32_e32 v140, s57, v169
	v_add_u32_e32 v148, s68, v169
	ds_read_b128 v[128:131], v140
	ds_read_b128 v[132:135], v140 offset:1024
	ds_read_b128 v[136:139], v140 offset:2048
	ds_read_b128 v[140:143], v140 offset:3072
	ds_read_b128 v[160:163], v148
	ds_read_b128 v[174:177], v148 offset:1024
	ds_read_b128 v[194:197], v148 offset:2048
	ds_read_b128 v[198:201], v148 offset:3072
	s_add_u32 s66, s66, 0x40000
	s_addc_u32 s67, s67, 0
	s_mov_b32 m0, s88
	v_lshl_add_u64 v[188:189], s[66:67], 0, v[144:145]
	ds_read_b128 v[202:205], v183 offset:32768
	ds_read_b128 v[206:209], v183 offset:33792
	ds_read_b128 v[210:213], v183 offset:34816
	ds_read_b128 v[214:217], v183 offset:35840
	ds_read_b128 v[218:221], v183 offset:36864
	ds_read_b128 v[222:225], v183 offset:37888
	ds_read_b128 v[226:229], v183 offset:38912
	ds_read_b128 v[230:233], v183 offset:39936
	global_load_lds_dwordx4 v[188:189], off
	v_lshl_add_u64 v[188:189], s[66:67], 0, v[146:147]
	s_mov_b32 m0, s89
	s_nop 0
	global_load_lds_dwordx4 v[188:189], off
	s_waitcnt vmcnt(8)
	s_waitcnt lgkmcnt(0)
	s_setprio 1
	s_barrier
	v_mfma_f32_16x16x32_bf16 v[124:127], v[128:131], v[202:205], v[124:127]
	v_mfma_f32_16x16x32_bf16 v[120:123], v[136:139], v[202:205], v[120:123]
	v_mfma_f32_16x16x32_bf16 v[108:111], v[128:131], v[210:213], v[108:111]
	v_mfma_f32_16x16x32_bf16 v[104:107], v[136:139], v[210:213], v[104:107]
	v_mfma_f32_16x16x32_bf16 v[92:95], v[128:131], v[218:221], v[92:95]
	v_mfma_f32_16x16x32_bf16 v[88:91], v[136:139], v[218:221], v[88:91]
	v_mfma_f32_16x16x32_bf16 v[76:79], v[128:131], v[226:229], v[76:79]
	v_mfma_f32_16x16x32_bf16 v[72:75], v[136:139], v[226:229], v[72:75]
	v_mfma_f32_16x16x32_bf16 v[124:127], v[132:135], v[206:209], v[124:127]
	v_mfma_f32_16x16x32_bf16 v[120:123], v[140:143], v[206:209], v[120:123]
	v_mfma_f32_16x16x32_bf16 v[108:111], v[132:135], v[214:217], v[108:111]
	v_mfma_f32_16x16x32_bf16 v[104:107], v[140:143], v[214:217], v[104:107]
	v_mfma_f32_16x16x32_bf16 v[92:95], v[132:135], v[222:225], v[92:95]
	v_mfma_f32_16x16x32_bf16 v[88:91], v[140:143], v[222:225], v[88:91]
	v_mfma_f32_16x16x32_bf16 v[76:79], v[132:135], v[230:233], v[76:79]
	v_mfma_f32_16x16x32_bf16 v[72:75], v[140:143], v[230:233], v[72:75]
	s_setprio 0
	s_setprio 1
	v_mfma_f32_16x16x32_bf16 v[116:119], v[160:163], v[202:205], v[116:119]
	v_mfma_f32_16x16x32_bf16 v[112:115], v[194:197], v[202:205], v[112:115]
	v_mfma_f32_16x16x32_bf16 v[100:103], v[160:163], v[210:213], v[100:103]
	v_mfma_f32_16x16x32_bf16 v[96:99], v[194:197], v[210:213], v[96:99]
	v_mfma_f32_16x16x32_bf16 v[84:87], v[160:163], v[218:221], v[84:87]
	v_mfma_f32_16x16x32_bf16 v[80:83], v[194:197], v[218:221], v[80:83]
	v_mfma_f32_16x16x32_bf16 v[68:71], v[160:163], v[226:229], v[68:71]
	v_mfma_f32_16x16x32_bf16 v[64:67], v[194:197], v[226:229], v[64:67]
	v_mfma_f32_16x16x32_bf16 v[116:119], v[174:177], v[206:209], v[116:119]
	v_mfma_f32_16x16x32_bf16 v[112:115], v[198:201], v[206:209], v[112:115]
	v_mfma_f32_16x16x32_bf16 v[100:103], v[174:177], v[214:217], v[100:103]
	v_mfma_f32_16x16x32_bf16 v[96:99], v[198:201], v[214:217], v[96:99]
	v_mfma_f32_16x16x32_bf16 v[84:87], v[174:177], v[222:225], v[84:87]
	v_mfma_f32_16x16x32_bf16 v[80:83], v[198:201], v[222:225], v[80:83]
	v_mfma_f32_16x16x32_bf16 v[68:71], v[174:177], v[230:233], v[68:71]
	v_mfma_f32_16x16x32_bf16 v[64:67], v[198:201], v[230:233], v[64:67]
	s_barrier
	s_setprio 0
	s_add_i32 s57, s57, s85
	v_lshl_add_u64 v[166:167], v[166:167], 0, s[42:43]
	s_mov_b32 m0, s57
	ds_read_b128 v[202:205], v183 offset:49152
	ds_read_b128 v[206:209], v183 offset:50176
	ds_read_b128 v[210:213], v183 offset:51200
	ds_read_b128 v[214:217], v183 offset:52224
	ds_read_b128 v[218:221], v183 offset:53248
	ds_read_b128 v[222:225], v183 offset:54272
	ds_read_b128 v[226:229], v183 offset:55296
	ds_read_b128 v[230:233], v183 offset:56320
	global_load_lds_dwordx4 v[166:167], off
	s_add_i32 m0, s57, 0x2000
	s_add_u32 s64, s64, 0x40080
	v_lshl_add_u64 v[166:167], v[170:171], 0, s[42:43]
	s_addc_u32 s65, s65, 0
	s_add_i32 s57, s68, s85
	global_load_lds_dwordx4 v[166:167], off
	v_lshl_add_u64 v[166:167], s[64:65], 0, v[144:145]
	s_mov_b32 m0, s57
	s_nop 0
	global_load_lds_dwordx4 v[166:167], off
	v_lshl_add_u64 v[166:167], s[64:65], 0, v[146:147]
	s_add_i32 m0, s57, 0x2000
	s_nop 0
	global_load_lds_dwordx4 v[166:167], off
	v_lshl_add_u64 v[166:167], v[180:181], 0, s[42:43]
	s_mov_b32 m0, s94
	s_nop 0
	global_load_lds_dwordx4 v[166:167], off
	v_lshl_add_u64 v[166:167], v[184:185], 0, s[42:43]
	s_mov_b32 m0, s95
	s_nop 0
	global_load_lds_dwordx4 v[166:167], off
	s_waitcnt vmcnt(8)
	s_waitcnt lgkmcnt(0)
	s_setprio 1
	s_barrier
	v_mfma_f32_16x16x32_bf16 v[60:63], v[128:131], v[202:205], v[60:63]
	v_mfma_f32_16x16x32_bf16 v[56:59], v[136:139], v[202:205], v[56:59]
	v_mfma_f32_16x16x32_bf16 v[44:47], v[128:131], v[210:213], v[44:47]
	v_mfma_f32_16x16x32_bf16 v[40:43], v[136:139], v[210:213], v[40:43]
	v_mfma_f32_16x16x32_bf16 v[28:31], v[128:131], v[218:221], v[28:31]
	v_mfma_f32_16x16x32_bf16 v[24:27], v[136:139], v[218:221], v[24:27]
	v_mfma_f32_16x16x32_bf16 v[12:15], v[128:131], v[226:229], v[12:15]
	v_mfma_f32_16x16x32_bf16 v[8:11], v[136:139], v[226:229], v[8:11]
	v_mfma_f32_16x16x32_bf16 v[60:63], v[132:135], v[206:209], v[60:63]
	v_mfma_f32_16x16x32_bf16 v[56:59], v[140:143], v[206:209], v[56:59]
	v_mfma_f32_16x16x32_bf16 v[44:47], v[132:135], v[214:217], v[44:47]
	v_mfma_f32_16x16x32_bf16 v[40:43], v[140:143], v[214:217], v[40:43]
	v_mfma_f32_16x16x32_bf16 v[28:31], v[132:135], v[222:225], v[28:31]
	v_mfma_f32_16x16x32_bf16 v[24:27], v[140:143], v[222:225], v[24:27]
	v_mfma_f32_16x16x32_bf16 v[12:15], v[132:135], v[230:233], v[12:15]
	v_mfma_f32_16x16x32_bf16 v[8:11], v[140:143], v[230:233], v[8:11]
	s_setprio 0
	s_setprio 1
	v_mfma_f32_16x16x32_bf16 v[52:55], v[160:163], v[202:205], v[52:55]
	v_mfma_f32_16x16x32_bf16 v[48:51], v[194:197], v[202:205], v[48:51]
	v_mfma_f32_16x16x32_bf16 v[36:39], v[160:163], v[210:213], v[36:39]
	v_mfma_f32_16x16x32_bf16 v[32:35], v[194:197], v[210:213], v[32:35]
	v_mfma_f32_16x16x32_bf16 v[20:23], v[160:163], v[218:221], v[20:23]
	v_mfma_f32_16x16x32_bf16 v[16:19], v[194:197], v[218:221], v[16:19]
	v_mfma_f32_16x16x32_bf16 v[4:7], v[160:163], v[226:229], v[4:7]
	v_mfma_f32_16x16x32_bf16 v[0:3], v[194:197], v[226:229], v[0:3]
	v_mfma_f32_16x16x32_bf16 v[52:55], v[174:177], v[206:209], v[52:55]
	v_mfma_f32_16x16x32_bf16 v[48:51], v[198:201], v[206:209], v[48:51]
	v_mfma_f32_16x16x32_bf16 v[36:39], v[174:177], v[214:217], v[36:39]
	v_mfma_f32_16x16x32_bf16 v[32:35], v[198:201], v[214:217], v[32:35]
	v_mfma_f32_16x16x32_bf16 v[20:23], v[174:177], v[222:225], v[20:23]
	v_mfma_f32_16x16x32_bf16 v[16:19], v[198:201], v[222:225], v[16:19]
	v_mfma_f32_16x16x32_bf16 v[4:7], v[174:177], v[230:233], v[4:7]
	v_mfma_f32_16x16x32_bf16 v[0:3], v[198:201], v[230:233], v[0:3]
	s_barrier
	s_setprio 0
	s_add_i32 s55, s55, 2
	s_add_u32 s62, s62, 0x100
	s_addc_u32 s63, s63, 0
	s_add_u32 s22, s22, 0x100
	s_addc_u32 s23, s23, 0
	s_cmp_gt_u32 s55, 13
	s_cbranch_scc0 .LBB0_552
	s_and_b64 vcc, exec, s[44:45]
	s_cbranch_vccz .LBB0_555
	s_barrier

.Lkv_nopf:
	s_barrier
	v_mfma_f32_16x16x32_bf16 v[124:127], v[150:153], v[182:185], v[124:127]
	v_mfma_f32_16x16x32_bf16 v[120:123], v[158:161], v[182:185], v[120:123]
	v_mfma_f32_16x16x32_bf16 v[108:111], v[150:153], v[190:193], v[108:111]
	v_mfma_f32_16x16x32_bf16 v[104:107], v[158:161], v[190:193], v[104:107]
	v_mfma_f32_16x16x32_bf16 v[92:95], v[150:153], v[198:201], v[92:95]
	v_mfma_f32_16x16x32_bf16 v[88:91], v[158:161], v[198:201], v[88:91]
	v_mfma_f32_16x16x32_bf16 v[76:79], v[150:153], v[206:209], v[76:79]
	v_mfma_f32_16x16x32_bf16 v[72:75], v[158:161], v[206:209], v[72:75]
	v_mfma_f32_16x16x32_bf16 v[124:127], v[154:157], v[186:189], v[124:127]
	v_mfma_f32_16x16x32_bf16 v[120:123], v[162:165], v[186:189], v[120:123]
	v_mfma_f32_16x16x32_bf16 v[108:111], v[154:157], v[194:197], v[108:111]
	v_mfma_f32_16x16x32_bf16 v[104:107], v[162:165], v[194:197], v[104:107]
	v_mfma_f32_16x16x32_bf16 v[92:95], v[154:157], v[202:205], v[92:95]
	v_mfma_f32_16x16x32_bf16 v[88:91], v[162:165], v[202:205], v[88:91]
	v_mfma_f32_16x16x32_bf16 v[76:79], v[154:157], v[210:213], v[76:79]
	v_mfma_f32_16x16x32_bf16 v[72:75], v[162:165], v[210:213], v[72:75]
	s_setprio 0
	s_setprio 1
	v_mfma_f32_16x16x32_bf16 v[116:119], v[166:169], v[182:185], v[116:119]
	v_mfma_f32_16x16x32_bf16 v[112:115], v[174:177], v[182:185], v[112:115]
	v_mfma_f32_16x16x32_bf16 v[100:103], v[166:169], v[190:193], v[100:103]
	v_mfma_f32_16x16x32_bf16 v[96:99], v[174:177], v[190:193], v[96:99]
	v_mfma_f32_16x16x32_bf16 v[84:87], v[166:169], v[198:201], v[84:87]
	v_mfma_f32_16x16x32_bf16 v[80:83], v[174:177], v[198:201], v[80:83]
	v_mfma_f32_16x16x32_bf16 v[68:71], v[166:169], v[206:209], v[68:71]
	v_mfma_f32_16x16x32_bf16 v[64:67], v[174:177], v[206:209], v[64:67]
	v_mfma_f32_16x16x32_bf16 v[116:119], v[170:173], v[186:189], v[116:119]
	v_mfma_f32_16x16x32_bf16 v[112:115], v[178:181], v[186:189], v[112:115]
	v_mfma_f32_16x16x32_bf16 v[100:103], v[170:173], v[194:197], v[100:103]
	v_mfma_f32_16x16x32_bf16 v[96:99], v[178:181], v[194:197], v[96:99]
	v_mfma_f32_16x16x32_bf16 v[84:87], v[170:173], v[202:205], v[84:87]
	v_mfma_f32_16x16x32_bf16 v[80:83], v[178:181], v[202:205], v[80:83]
	v_mfma_f32_16x16x32_bf16 v[68:71], v[170:173], v[210:213], v[68:71]
	v_mfma_f32_16x16x32_bf16 v[64:67], v[178:181], v[210:213], v[64:67]
	s_barrier
	s_setprio 0
	s_mov_b32 m0, s93
	v_lshl_add_u64 v[138:139], s[52:53], 0, v[130:131]
	ds_read_b128 v[182:185], v146 offset:16384
	ds_read_b128 v[186:189], v146 offset:17408
	ds_read_b128 v[190:193], v146 offset:18432
	ds_read_b128 v[194:197], v146 offset:19456
	ds_read_b128 v[198:201], v146 offset:20480
	ds_read_b128 v[202:205], v146 offset:21504
	ds_read_b128 v[206:209], v146 offset:22528
	ds_read_b128 v[210:213], v146 offset:23552
	global_load_lds_dwordx4 v[138:139], off
	v_lshl_add_u64 v[214:215], s[52:53], 0, v[128:129]
	s_mov_b32 m0, s90
	v_lshl_add_u64 v[216:217], s[54:55], 0, v[130:131]
	global_load_lds_dwordx4 v[214:215], off
	s_mov_b32 m0, s92
	v_lshl_add_u64 v[218:219], s[50:51], 0, v[128:129]
	global_load_lds_dwordx4 v[216:217], off
	v_lshl_add_u64 v[216:217], s[54:55], 0, v[128:129]
	s_mov_b32 m0, s91
	s_nop 0
	global_load_lds_dwordx4 v[216:217], off
	v_lshl_add_u64 v[216:217], s[50:51], 0, v[130:131]
	s_mov_b32 m0, s61
	s_nop 0
	global_load_lds_dwordx4 v[216:217], off
	s_mov_b32 m0, s62
	s_nop 0
	global_load_lds_dwordx4 v[218:219], off
	s_waitcnt vmcnt(8)
	s_waitcnt lgkmcnt(0)
	s_setprio 1
	s_barrier
	v_mfma_f32_16x16x32_bf16 v[60:63], v[150:153], v[182:185], v[60:63]
	v_mfma_f32_16x16x32_bf16 v[56:59], v[158:161], v[182:185], v[56:59]
	v_mfma_f32_16x16x32_bf16 v[44:47], v[150:153], v[190:193], v[44:47]
	v_mfma_f32_16x16x32_bf16 v[40:43], v[158:161], v[190:193], v[40:43]
	v_mfma_f32_16x16x32_bf16 v[28:31], v[150:153], v[198:201], v[28:31]
	v_mfma_f32_16x16x32_bf16 v[24:27], v[158:161], v[198:201], v[24:27]
	v_mfma_f32_16x16x32_bf16 v[12:15], v[150:153], v[206:209], v[12:15]
	v_mfma_f32_16x16x32_bf16 v[8:11], v[158:161], v[206:209], v[8:11]
	v_mfma_f32_16x16x32_bf16 v[60:63], v[154:157], v[186:189], v[60:63]
	v_mfma_f32_16x16x32_bf16 v[56:59], v[162:165], v[186:189], v[56:59]
	v_mfma_f32_16x16x32_bf16 v[44:47], v[154:157], v[194:197], v[44:47]
	v_mfma_f32_16x16x32_bf16 v[40:43], v[162:165], v[194:197], v[40:43]
	v_mfma_f32_16x16x32_bf16 v[28:31], v[154:157], v[202:205], v[28:31]
	v_mfma_f32_16x16x32_bf16 v[24:27], v[162:165], v[202:205], v[24:27]
	v_mfma_f32_16x16x32_bf16 v[12:15], v[154:157], v[210:213], v[12:15]
	v_mfma_f32_16x16x32_bf16 v[8:11], v[162:165], v[210:213], v[8:11]
	s_setprio 0
	s_setprio 1
	v_mfma_f32_16x16x32_bf16 v[52:55], v[166:169], v[182:185], v[52:55]
	v_mfma_f32_16x16x32_bf16 v[48:51], v[174:177], v[182:185], v[48:51]
	v_mfma_f32_16x16x32_bf16 v[36:39], v[166:169], v[190:193], v[36:39]
	v_mfma_f32_16x16x32_bf16 v[32:35], v[174:177], v[190:193], v[32:35]
	v_mfma_f32_16x16x32_bf16 v[20:23], v[166:169], v[198:201], v[20:23]
	v_mfma_f32_16x16x32_bf16 v[16:19], v[174:177], v[198:201], v[16:19]
	v_mfma_f32_16x16x32_bf16 v[4:7], v[166:169], v[206:209], v[4:7]
	v_mfma_f32_16x16x32_bf16 v[0:3], v[174:177], v[206:209], v[0:3]
	v_mfma_f32_16x16x32_bf16 v[52:55], v[170:173], v[186:189], v[52:55]
	v_mfma_f32_16x16x32_bf16 v[48:51], v[178:181], v[186:189], v[48:51]
	v_mfma_f32_16x16x32_bf16 v[36:39], v[170:173], v[194:197], v[36:39]
	v_mfma_f32_16x16x32_bf16 v[32:35], v[178:181], v[194:197], v[32:35]
	v_mfma_f32_16x16x32_bf16 v[20:23], v[170:173], v[202:205], v[20:23]
	v_mfma_f32_16x16x32_bf16 v[16:19], v[178:181], v[202:205], v[16:19]
	v_mfma_f32_16x16x32_bf16 v[4:7], v[170:173], v[210:213], v[4:7]
	v_mfma_f32_16x16x32_bf16 v[0:3], v[178:181], v[210:213], v[0:3]
	s_barrier
	s_setprio 0
	v_add_u32_e32 v132, s89, v143
	ds_read_b128 v[150:153], v132
	ds_read_b128 v[154:157], v132 offset:1024
	ds_read_b128 v[158:161], v132 offset:2048
	ds_read_b128 v[162:165], v132 offset:3072
	v_add_u32_e32 v132, s88, v143
	ds_read_b128 v[166:169], v132
	ds_read_b128 v[170:173], v132 offset:1024
	ds_read_b128 v[174:177], v132 offset:2048
	ds_read_b128 v[178:181], v132 offset:3072
	s_mov_b32 m0, s63
	v_lshl_add_u64 v[220:221], s[48:49], 0, v[130:131]
	ds_read_b128 v[182:185], v146 offset:32768
	ds_read_b128 v[186:189], v146 offset:33792
	ds_read_b128 v[190:193], v146 offset:34816
	ds_read_b128 v[194:197], v146 offset:35840
	ds_read_b128 v[198:201], v146 offset:36864
	ds_read_b128 v[202:205], v146 offset:37888
	ds_read_b128 v[206:209], v146 offset:38912
	ds_read_b128 v[210:213], v146 offset:39936
	global_load_lds_dwordx4 v[220:221], off
	v_lshl_add_u64 v[220:221], s[48:49], 0, v[128:129]
	s_mov_b32 m0, s64
	s_nop 0
	global_load_lds_dwordx4 v[220:221], off
	s_waitcnt vmcnt(8)
	s_waitcnt lgkmcnt(0)
	s_setprio 1
	s_barrier
	v_mfma_f32_16x16x32_bf16 v[124:127], v[150:153], v[182:185], v[124:127]
	v_mfma_f32_16x16x32_bf16 v[120:123], v[158:161], v[182:185], v[120:123]
	v_mfma_f32_16x16x32_bf16 v[108:111], v[150:153], v[190:193], v[108:111]
	v_mfma_f32_16x16x32_bf16 v[104:107], v[158:161], v[190:193], v[104:107]
	v_mfma_f32_16x16x32_bf16 v[92:95], v[150:153], v[198:201], v[92:95]
	v_mfma_f32_16x16x32_bf16 v[88:91], v[158:161], v[198:201], v[88:91]
	v_mfma_f32_16x16x32_bf16 v[76:79], v[150:153], v[206:209], v[76:79]
	v_mfma_f32_16x16x32_bf16 v[72:75], v[158:161], v[206:209], v[72:75]
	v_mfma_f32_16x16x32_bf16 v[124:127], v[154:157], v[186:189], v[124:127]
	v_mfma_f32_16x16x32_bf16 v[120:123], v[162:165], v[186:189], v[120:123]
	v_mfma_f32_16x16x32_bf16 v[108:111], v[154:157], v[194:197], v[108:111]
	v_mfma_f32_16x16x32_bf16 v[104:107], v[162:165], v[194:197], v[104:107]
	v_mfma_f32_16x16x32_bf16 v[92:95], v[154:157], v[202:205], v[92:95]
	v_mfma_f32_16x16x32_bf16 v[88:91], v[162:165], v[202:205], v[88:91]
	v_mfma_f32_16x16x32_bf16 v[76:79], v[154:157], v[210:213], v[76:79]
	v_mfma_f32_16x16x32_bf16 v[72:75], v[162:165], v[210:213], v[72:75]
	s_setprio 0
	s_setprio 1
	v_mfma_f32_16x16x32_bf16 v[116:119], v[166:169], v[182:185], v[116:119]
	v_mfma_f32_16x16x32_bf16 v[112:115], v[174:177], v[182:185], v[112:115]
	v_mfma_f32_16x16x32_bf16 v[100:103], v[166:169], v[190:193], v[100:103]
	v_mfma_f32_16x16x32_bf16 v[96:99], v[174:177], v[190:193], v[96:99]
	v_mfma_f32_16x16x32_bf16 v[84:87], v[166:169], v[198:201], v[84:87]
	v_mfma_f32_16x16x32_bf16 v[80:83], v[174:177], v[198:201], v[80:83]
	v_mfma_f32_16x16x32_bf16 v[68:71], v[166:169], v[206:209], v[68:71]
	v_mfma_f32_16x16x32_bf16 v[64:67], v[174:177], v[206:209], v[64:67]
	v_mfma_f32_16x16x32_bf16 v[116:119], v[170:173], v[186:189], v[116:119]
	v_mfma_f32_16x16x32_bf16 v[112:115], v[178:181], v[186:189], v[112:115]
	v_mfma_f32_16x16x32_bf16 v[100:103], v[170:173], v[194:197], v[100:103]
	v_mfma_f32_16x16x32_bf16 v[96:99], v[178:181], v[194:197], v[96:99]
	v_mfma_f32_16x16x32_bf16 v[84:87], v[170:173], v[202:205], v[84:87]
	v_mfma_f32_16x16x32_bf16 v[80:83], v[178:181], v[202:205], v[80:83]
	v_mfma_f32_16x16x32_bf16 v[68:71], v[170:173], v[210:213], v[68:71]
	v_mfma_f32_16x16x32_bf16 v[64:67], v[178:181], v[210:213], v[64:67]
	s_barrier
	s_setprio 0
	s_mov_b32 m0, s87
	v_lshl_add_u64 v[138:139], v[138:139], 0, s[16:17]
	ds_read_b128 v[182:185], v146 offset:49152
	ds_read_b128 v[186:189], v146 offset:50176
	ds_read_b128 v[190:193], v146 offset:51200
	ds_read_b128 v[194:197], v146 offset:52224
	ds_read_b128 v[198:201], v146 offset:53248
	ds_read_b128 v[202:205], v146 offset:54272
	ds_read_b128 v[206:209], v146 offset:55296
	ds_read_b128 v[210:213], v146 offset:56320
	global_load_lds_dwordx4 v[138:139], off
	v_lshl_add_u64 v[138:139], v[214:215], 0, s[16:17]
	s_mov_b32 m0, s85
	s_nop 0
	global_load_lds_dwordx4 v[138:139], off
	v_lshl_add_u64 v[138:139], s[46:47], 0, v[130:131]
	s_mov_b32 m0, s86
	s_nop 0
	global_load_lds_dwordx4 v[138:139], off
	v_lshl_add_u64 v[138:139], s[46:47], 0, v[128:129]
	s_mov_b32 m0, s84
	s_nop 0
	global_load_lds_dwordx4 v[138:139], off
	v_lshl_add_u64 v[138:139], v[216:217], 0, s[16:17]
	s_mov_b32 m0, s70
	s_nop 0
	global_load_lds_dwordx4 v[138:139], off
	v_lshl_add_u64 v[138:139], v[218:219], 0, s[16:17]
	s_mov_b32 m0, s71
	s_nop 0
	global_load_lds_dwordx4 v[138:139], off
	s_waitcnt vmcnt(8)
	s_waitcnt lgkmcnt(0)
	s_setprio 1
	s_barrier
	v_mfma_f32_16x16x32_bf16 v[60:63], v[150:153], v[182:185], v[60:63]
	v_mfma_f32_16x16x32_bf16 v[56:59], v[158:161], v[182:185], v[56:59]
	v_mfma_f32_16x16x32_bf16 v[44:47], v[150:153], v[190:193], v[44:47]
	v_mfma_f32_16x16x32_bf16 v[40:43], v[158:161], v[190:193], v[40:43]
	v_mfma_f32_16x16x32_bf16 v[28:31], v[150:153], v[198:201], v[28:31]
	v_mfma_f32_16x16x32_bf16 v[24:27], v[158:161], v[198:201], v[24:27]
	v_mfma_f32_16x16x32_bf16 v[12:15], v[150:153], v[206:209], v[12:15]
	v_mfma_f32_16x16x32_bf16 v[8:11], v[158:161], v[206:209], v[8:11]
	v_mfma_f32_16x16x32_bf16 v[60:63], v[154:157], v[186:189], v[60:63]
	v_mfma_f32_16x16x32_bf16 v[56:59], v[162:165], v[186:189], v[56:59]
	v_mfma_f32_16x16x32_bf16 v[44:47], v[154:157], v[194:197], v[44:47]
	v_mfma_f32_16x16x32_bf16 v[40:43], v[162:165], v[194:197], v[40:43]
	v_mfma_f32_16x16x32_bf16 v[28:31], v[154:157], v[202:205], v[28:31]
	v_mfma_f32_16x16x32_bf16 v[24:27], v[162:165], v[202:205], v[24:27]
	v_mfma_f32_16x16x32_bf16 v[12:15], v[154:157], v[210:213], v[12:15]
	v_mfma_f32_16x16x32_bf16 v[8:11], v[162:165], v[210:213], v[8:11]
	s_setprio 0
	s_setprio 1
	v_mfma_f32_16x16x32_bf16 v[52:55], v[166:169], v[182:185], v[52:55]
	v_mfma_f32_16x16x32_bf16 v[48:51], v[174:177], v[182:185], v[48:51]
	v_mfma_f32_16x16x32_bf16 v[36:39], v[166:169], v[190:193], v[36:39]
	v_mfma_f32_16x16x32_bf16 v[32:35], v[174:177], v[190:193], v[32:35]
	v_mfma_f32_16x16x32_bf16 v[20:23], v[166:169], v[198:201], v[20:23]
	v_mfma_f32_16x16x32_bf16 v[16:19], v[174:177], v[198:201], v[16:19]
	v_mfma_f32_16x16x32_bf16 v[4:7], v[166:169], v[206:209], v[4:7]
	v_mfma_f32_16x16x32_bf16 v[0:3], v[174:177], v[206:209], v[0:3]
	v_mfma_f32_16x16x32_bf16 v[52:55], v[170:173], v[186:189], v[52:55]
	v_mfma_f32_16x16x32_bf16 v[48:51], v[178:181], v[186:189], v[48:51]
	v_mfma_f32_16x16x32_bf16 v[36:39], v[170:173], v[194:197], v[36:39]
	v_mfma_f32_16x16x32_bf16 v[32:35], v[178:181], v[194:197], v[32:35]
	v_mfma_f32_16x16x32_bf16 v[20:23], v[170:173], v[202:205], v[20:23]
	v_mfma_f32_16x16x32_bf16 v[16:19], v[178:181], v[202:205], v[16:19]
	v_mfma_f32_16x16x32_bf16 v[4:7], v[170:173], v[210:213], v[4:7]
	v_mfma_f32_16x16x32_bf16 v[0:3], v[178:181], v[210:213], v[0:3]
	s_barrier
	s_setprio 0
	s_andn2_b64 vcc, exec, s[44:45]
	s_mov_b64 s[46:47], -1
	s_mov_b64 s[44:45], 0
	s_mov_b64 s[48:49], 0x100
	s_cbranch_vccz .LBB0_744
	s_and_b64 vcc, exec, s[20:21]
	s_cbranch_vccz .LBB0_747
	s_barrier

.LBB0_771:
	ds_read_b128 v[84:87], v208
	ds_read_b128 v[100:103], v208 offset:1024
	ds_read_b128 v[120:123], v208 offset:2048
	ds_read_b128 v[140:143], v208 offset:3072
	ds_read_b128 v[144:147], v209
	ds_read_b128 v[148:151], v209 offset:1024
	ds_read_b128 v[152:155], v209 offset:2048
	ds_read_b128 v[170:173], v209 offset:3072
	s_add_u32 s6, s8, 0x100
	s_addc_u32 s7, s9, 0
	s_cmp_eq_u32 s83, 2
	s_cselect_b32 s41, s35, s7
	s_cselect_b32 s40, s34, s6
	s_cselect_b32 s39, s37, s82
	s_cselect_b32 s38, s36, s81
	v_lshl_add_u64 v[214:215], s[8:9], 0, v[162:163]
	s_add_i32 m0, s42, 0xc000
	ds_read_b128 v[174:177], v210
	ds_read_b128 v[178:181], v210 offset:1024
	ds_read_b128 v[182:185], v210 offset:2048
	ds_read_b128 v[186:189], v210 offset:3072
	ds_read_b128 v[190:193], v210 offset:4096
	ds_read_b128 v[194:197], v210 offset:5120
	ds_read_b128 v[198:201], v210 offset:6144
	ds_read_b128 v[202:205], v210 offset:7168
	global_load_lds_dwordx4 v[214:215], off
	v_lshl_add_u64 v[214:215], s[8:9], 0, v[164:165]
	s_add_i32 m0, s42, 0xe000
	s_nop 0
	global_load_lds_dwordx4 v[214:215], off
	s_waitcnt vmcnt(8)
	s_waitcnt lgkmcnt(0)
	s_setprio 1
	s_barrier
	v_mfma_f32_16x16x32_bf16 v[136:139], v[84:87], v[174:177], v[136:139]
	v_mfma_f32_16x16x32_bf16 v[132:135], v[120:123], v[174:177], v[132:135]
	v_mfma_f32_16x16x32_bf16 v[116:119], v[84:87], v[182:185], v[116:119]
	v_mfma_f32_16x16x32_bf16 v[112:115], v[120:123], v[182:185], v[112:115]
	v_mfma_f32_16x16x32_bf16 v[96:99], v[84:87], v[190:193], v[96:99]
	v_mfma_f32_16x16x32_bf16 v[92:95], v[120:123], v[190:193], v[92:95]
	v_mfma_f32_16x16x32_bf16 v[76:79], v[84:87], v[198:201], v[76:79]
	v_mfma_f32_16x16x32_bf16 v[72:75], v[120:123], v[198:201], v[72:75]
	v_mfma_f32_16x16x32_bf16 v[136:139], v[100:103], v[178:181], v[136:139]
	v_mfma_f32_16x16x32_bf16 v[132:135], v[140:143], v[178:181], v[132:135]
	v_mfma_f32_16x16x32_bf16 v[116:119], v[100:103], v[186:189], v[116:119]
	v_mfma_f32_16x16x32_bf16 v[112:115], v[140:143], v[186:189], v[112:115]
	v_mfma_f32_16x16x32_bf16 v[96:99], v[100:103], v[194:197], v[96:99]
	v_mfma_f32_16x16x32_bf16 v[92:95], v[140:143], v[194:197], v[92:95]
	v_mfma_f32_16x16x32_bf16 v[76:79], v[100:103], v[202:205], v[76:79]
	v_mfma_f32_16x16x32_bf16 v[72:75], v[140:143], v[202:205], v[72:75]
	s_setprio 0
	s_setprio 1
	v_mfma_f32_16x16x32_bf16 v[128:131], v[144:147], v[174:177], v[128:131]
	v_mfma_f32_16x16x32_bf16 v[124:127], v[152:155], v[174:177], v[124:127]
	v_mfma_f32_16x16x32_bf16 v[108:111], v[144:147], v[182:185], v[108:111]
	v_mfma_f32_16x16x32_bf16 v[104:107], v[152:155], v[182:185], v[104:107]
	v_mfma_f32_16x16x32_bf16 v[88:91], v[144:147], v[190:193], v[88:91]
	v_mfma_f32_16x16x32_bf16 v[80:83], v[152:155], v[190:193], v[80:83]
	v_mfma_f32_16x16x32_bf16 v[68:71], v[144:147], v[198:201], v[68:71]
	v_mfma_f32_16x16x32_bf16 v[64:67], v[152:155], v[198:201], v[64:67]
	v_mfma_f32_16x16x32_bf16 v[128:131], v[148:151], v[178:181], v[128:131]
	v_mfma_f32_16x16x32_bf16 v[124:127], v[170:173], v[178:181], v[124:127]
	v_mfma_f32_16x16x32_bf16 v[108:111], v[148:151], v[186:189], v[108:111]
	v_mfma_f32_16x16x32_bf16 v[104:107], v[170:173], v[186:189], v[104:107]
	v_mfma_f32_16x16x32_bf16 v[88:91], v[148:151], v[194:197], v[88:91]
	v_mfma_f32_16x16x32_bf16 v[80:83], v[170:173], v[194:197], v[80:83]
	v_mfma_f32_16x16x32_bf16 v[68:71], v[148:151], v[202:205], v[68:71]
	v_mfma_f32_16x16x32_bf16 v[64:67], v[170:173], v[202:205], v[64:67]
	s_barrier
	s_setprio 0
	s_add_i32 s8, s61, s3
	v_lshl_add_u64 v[214:215], s[38:39], 0, v[156:157]
	s_mov_b32 m0, s8
	ds_read_b128 v[174:177], v210 offset:16384
	ds_read_b128 v[178:181], v210 offset:17408
	ds_read_b128 v[182:185], v210 offset:18432
	ds_read_b128 v[186:189], v210 offset:19456
	ds_read_b128 v[190:193], v210 offset:20480
	ds_read_b128 v[194:197], v210 offset:21504
	ds_read_b128 v[198:201], v210 offset:22528
	ds_read_b128 v[202:205], v210 offset:23552
	global_load_lds_dwordx4 v[214:215], off
	s_add_i32 m0, s8, 0x2000
	s_add_u32 s8, s38, 0x18000
	v_lshl_add_u64 v[216:217], s[38:39], 0, v[158:159]
	s_addc_u32 s9, s39, 0
	s_add_i32 s84, s62, s3
	global_load_lds_dwordx4 v[216:217], off
	v_lshl_add_u64 v[218:219], s[8:9], 0, v[156:157]
	s_mov_b32 m0, s84
	v_lshl_add_u64 v[220:221], s[40:41], 0, v[158:159]
	global_load_lds_dwordx4 v[218:219], off
	v_lshl_add_u64 v[218:219], s[8:9], 0, v[158:159]
	s_add_i32 m0, s84, 0x2000
	s_nop 0
	global_load_lds_dwordx4 v[218:219], off
	v_lshl_add_u64 v[218:219], s[40:41], 0, v[156:157]
	s_mov_b32 m0, s42
	s_nop 0
	global_load_lds_dwordx4 v[218:219], off
	s_mov_b32 m0, s43
	s_nop 0
	global_load_lds_dwordx4 v[220:221], off
	s_waitcnt vmcnt(8)
	s_waitcnt lgkmcnt(0)
	s_setprio 1
	s_barrier
	v_mfma_f32_16x16x32_bf16 v[60:63], v[84:87], v[174:177], v[60:63]
	v_mfma_f32_16x16x32_bf16 v[56:59], v[120:123], v[174:177], v[56:59]
	v_mfma_f32_16x16x32_bf16 v[44:47], v[84:87], v[182:185], v[44:47]
	v_mfma_f32_16x16x32_bf16 v[40:43], v[120:123], v[182:185], v[40:43]
	v_mfma_f32_16x16x32_bf16 v[28:31], v[84:87], v[190:193], v[28:31]
	v_mfma_f32_16x16x32_bf16 v[24:27], v[120:123], v[190:193], v[24:27]
	v_mfma_f32_16x16x32_bf16 v[12:15], v[84:87], v[198:201], v[12:15]
	v_mfma_f32_16x16x32_bf16 v[8:11], v[120:123], v[198:201], v[8:11]
	v_mfma_f32_16x16x32_bf16 v[60:63], v[100:103], v[178:181], v[60:63]
	v_mfma_f32_16x16x32_bf16 v[56:59], v[140:143], v[178:181], v[56:59]
	v_mfma_f32_16x16x32_bf16 v[44:47], v[100:103], v[186:189], v[44:47]
	v_mfma_f32_16x16x32_bf16 v[40:43], v[140:143], v[186:189], v[40:43]
	v_mfma_f32_16x16x32_bf16 v[28:31], v[100:103], v[194:197], v[28:31]
	v_mfma_f32_16x16x32_bf16 v[24:27], v[140:143], v[194:197], v[24:27]
	v_mfma_f32_16x16x32_bf16 v[12:15], v[100:103], v[202:205], v[12:15]
	v_mfma_f32_16x16x32_bf16 v[8:11], v[140:143], v[202:205], v[8:11]
	s_setprio 0
	s_setprio 1
	v_mfma_f32_16x16x32_bf16 v[52:55], v[144:147], v[174:177], v[52:55]
	v_mfma_f32_16x16x32_bf16 v[48:51], v[152:155], v[174:177], v[48:51]
	v_mfma_f32_16x16x32_bf16 v[36:39], v[144:147], v[182:185], v[36:39]
	v_mfma_f32_16x16x32_bf16 v[32:35], v[152:155], v[182:185], v[32:35]
	v_mfma_f32_16x16x32_bf16 v[20:23], v[144:147], v[190:193], v[20:23]
	v_mfma_f32_16x16x32_bf16 v[16:19], v[152:155], v[190:193], v[16:19]
	v_mfma_f32_16x16x32_bf16 v[4:7], v[144:147], v[198:201], v[4:7]
	v_mfma_f32_16x16x32_bf16 v[0:3], v[152:155], v[198:201], v[0:3]
	v_mfma_f32_16x16x32_bf16 v[52:55], v[148:151], v[178:181], v[52:55]
	v_mfma_f32_16x16x32_bf16 v[48:51], v[170:173], v[178:181], v[48:51]
	v_mfma_f32_16x16x32_bf16 v[36:39], v[148:151], v[186:189], v[36:39]
	v_mfma_f32_16x16x32_bf16 v[32:35], v[170:173], v[186:189], v[32:35]
	v_mfma_f32_16x16x32_bf16 v[20:23], v[148:151], v[194:197], v[20:23]
	v_mfma_f32_16x16x32_bf16 v[16:19], v[170:173], v[194:197], v[16:19]
	v_mfma_f32_16x16x32_bf16 v[4:7], v[148:151], v[202:205], v[4:7]
	v_mfma_f32_16x16x32_bf16 v[0:3], v[170:173], v[202:205], v[0:3]
	s_barrier
	s_setprio 0
	s_add_i32 s84, 0, 0x18000
	s_add_i32 s85, 0, 0x1c000
	v_add_u32_e32 v140, s84, v207
	v_add_u32_e32 v160, s85, v207
	ds_read_b128 v[84:87], v140
	ds_read_b128 v[100:103], v140 offset:1024
	ds_read_b128 v[120:123], v140 offset:2048
	ds_read_b128 v[140:143], v140 offset:3072
	ds_read_b128 v[144:147], v160
	ds_read_b128 v[148:151], v160 offset:1024
	ds_read_b128 v[152:155], v160 offset:2048
	ds_read_b128 v[170:173], v160 offset:3072
	s_add_u32 s8, s40, 0x18000
	s_addc_u32 s9, s41, 0
	s_mov_b32 m0, s44
	v_lshl_add_u64 v[222:223], s[8:9], 0, v[156:157]
	ds_read_b128 v[174:177], v210 offset:32768
	ds_read_b128 v[178:181], v210 offset:33792
	ds_read_b128 v[182:185], v210 offset:34816
	ds_read_b128 v[186:189], v210 offset:35840
	ds_read_b128 v[190:193], v210 offset:36864
	ds_read_b128 v[194:197], v210 offset:37888
	ds_read_b128 v[198:201], v210 offset:38912
	ds_read_b128 v[202:205], v210 offset:39936
	global_load_lds_dwordx4 v[222:223], off
	v_lshl_add_u64 v[222:223], s[8:9], 0, v[158:159]
	s_mov_b32 m0, s45
	s_nop 0
	global_load_lds_dwordx4 v[222:223], off
	s_waitcnt vmcnt(8)
	s_waitcnt lgkmcnt(0)
	s_setprio 1
	s_barrier
	v_mfma_f32_16x16x32_bf16 v[136:139], v[84:87], v[174:177], v[136:139]
	v_mfma_f32_16x16x32_bf16 v[132:135], v[120:123], v[174:177], v[132:135]
	v_mfma_f32_16x16x32_bf16 v[116:119], v[84:87], v[182:185], v[116:119]
	v_mfma_f32_16x16x32_bf16 v[112:115], v[120:123], v[182:185], v[112:115]
	v_mfma_f32_16x16x32_bf16 v[96:99], v[84:87], v[190:193], v[96:99]
	v_mfma_f32_16x16x32_bf16 v[92:95], v[120:123], v[190:193], v[92:95]
	v_mfma_f32_16x16x32_bf16 v[76:79], v[84:87], v[198:201], v[76:79]
	v_mfma_f32_16x16x32_bf16 v[72:75], v[120:123], v[198:201], v[72:75]
	v_mfma_f32_16x16x32_bf16 v[136:139], v[100:103], v[178:181], v[136:139]
	v_mfma_f32_16x16x32_bf16 v[132:135], v[140:143], v[178:181], v[132:135]
	v_mfma_f32_16x16x32_bf16 v[116:119], v[100:103], v[186:189], v[116:119]
	v_mfma_f32_16x16x32_bf16 v[112:115], v[140:143], v[186:189], v[112:115]
	v_mfma_f32_16x16x32_bf16 v[96:99], v[100:103], v[194:197], v[96:99]
	v_mfma_f32_16x16x32_bf16 v[92:95], v[140:143], v[194:197], v[92:95]
	v_mfma_f32_16x16x32_bf16 v[76:79], v[100:103], v[202:205], v[76:79]
	v_mfma_f32_16x16x32_bf16 v[72:75], v[140:143], v[202:205], v[72:75]
	s_setprio 0
	s_setprio 1
	v_mfma_f32_16x16x32_bf16 v[128:131], v[144:147], v[174:177], v[128:131]
	v_mfma_f32_16x16x32_bf16 v[124:127], v[152:155], v[174:177], v[124:127]
	v_mfma_f32_16x16x32_bf16 v[108:111], v[144:147], v[182:185], v[108:111]
	v_mfma_f32_16x16x32_bf16 v[104:107], v[152:155], v[182:185], v[104:107]
	v_mfma_f32_16x16x32_bf16 v[88:91], v[144:147], v[190:193], v[88:91]
	v_mfma_f32_16x16x32_bf16 v[80:83], v[152:155], v[190:193], v[80:83]
	v_mfma_f32_16x16x32_bf16 v[68:71], v[144:147], v[198:201], v[68:71]
	v_mfma_f32_16x16x32_bf16 v[64:67], v[152:155], v[198:201], v[64:67]
	v_mfma_f32_16x16x32_bf16 v[128:131], v[148:151], v[178:181], v[128:131]
	v_mfma_f32_16x16x32_bf16 v[124:127], v[170:173], v[178:181], v[124:127]
	v_mfma_f32_16x16x32_bf16 v[108:111], v[148:151], v[186:189], v[108:111]
	v_mfma_f32_16x16x32_bf16 v[104:107], v[170:173], v[186:189], v[104:107]
	v_mfma_f32_16x16x32_bf16 v[88:91], v[148:151], v[194:197], v[88:91]
	v_mfma_f32_16x16x32_bf16 v[80:83], v[170:173], v[194:197], v[80:83]
	v_mfma_f32_16x16x32_bf16 v[68:71], v[148:151], v[202:205], v[68:71]
	v_mfma_f32_16x16x32_bf16 v[64:67], v[170:173], v[202:205], v[64:67]
	s_barrier
	s_setprio 0
	s_add_i32 s8, s84, s3
	v_lshl_add_u64 v[214:215], v[214:215], 0, s[20:21]
	s_mov_b32 m0, s8
	ds_read_b128 v[174:177], v210 offset:49152
	ds_read_b128 v[178:181], v210 offset:50176
	ds_read_b128 v[182:185], v210 offset:51200
	ds_read_b128 v[186:189], v210 offset:52224
	ds_read_b128 v[190:193], v210 offset:53248
	ds_read_b128 v[194:197], v210 offset:54272
	ds_read_b128 v[198:201], v210 offset:55296
	ds_read_b128 v[202:205], v210 offset:56320
	global_load_lds_dwordx4 v[214:215], off
	s_add_i32 m0, s8, 0x2000
	s_add_u32 s8, s38, 0x18080
	v_lshl_add_u64 v[214:215], v[216:217], 0, s[20:21]
	s_addc_u32 s9, s39, 0
	s_add_i32 s38, s85, s3
	global_load_lds_dwordx4 v[214:215], off
	v_lshl_add_u64 v[214:215], s[8:9], 0, v[156:157]
	s_mov_b32 m0, s38
	s_nop 0
	global_load_lds_dwordx4 v[214:215], off
	v_lshl_add_u64 v[214:215], s[8:9], 0, v[158:159]
	s_add_i32 m0, s38, 0x2000
	s_nop 0
	global_load_lds_dwordx4 v[214:215], off
	v_lshl_add_u64 v[214:215], v[218:219], 0, s[20:21]
	s_mov_b32 m0, s51
	s_nop 0
	global_load_lds_dwordx4 v[214:215], off
	v_lshl_add_u64 v[214:215], v[220:221], 0, s[20:21]
	s_mov_b32 m0, s52
	s_nop 0
	global_load_lds_dwordx4 v[214:215], off
	s_waitcnt vmcnt(8)
	s_waitcnt lgkmcnt(0)
	s_setprio 1
	s_barrier
	v_mfma_f32_16x16x32_bf16 v[60:63], v[84:87], v[174:177], v[60:63]
	v_mfma_f32_16x16x32_bf16 v[56:59], v[120:123], v[174:177], v[56:59]
	v_mfma_f32_16x16x32_bf16 v[44:47], v[84:87], v[182:185], v[44:47]
	v_mfma_f32_16x16x32_bf16 v[40:43], v[120:123], v[182:185], v[40:43]
	v_mfma_f32_16x16x32_bf16 v[28:31], v[84:87], v[190:193], v[28:31]
	v_mfma_f32_16x16x32_bf16 v[24:27], v[120:123], v[190:193], v[24:27]
	v_mfma_f32_16x16x32_bf16 v[12:15], v[84:87], v[198:201], v[12:15]
	v_mfma_f32_16x16x32_bf16 v[8:11], v[120:123], v[198:201], v[8:11]
	v_mfma_f32_16x16x32_bf16 v[60:63], v[100:103], v[178:181], v[60:63]
	v_mfma_f32_16x16x32_bf16 v[56:59], v[140:143], v[178:181], v[56:59]
	v_mfma_f32_16x16x32_bf16 v[44:47], v[100:103], v[186:189], v[44:47]
	v_mfma_f32_16x16x32_bf16 v[40:43], v[140:143], v[186:189], v[40:43]
	v_mfma_f32_16x16x32_bf16 v[28:31], v[100:103], v[194:197], v[28:31]
	v_mfma_f32_16x16x32_bf16 v[24:27], v[140:143], v[194:197], v[24:27]
	v_mfma_f32_16x16x32_bf16 v[12:15], v[100:103], v[202:205], v[12:15]
	v_mfma_f32_16x16x32_bf16 v[8:11], v[140:143], v[202:205], v[8:11]
	s_setprio 0
	s_setprio 1
	v_mfma_f32_16x16x32_bf16 v[52:55], v[144:147], v[174:177], v[52:55]
	v_mfma_f32_16x16x32_bf16 v[48:51], v[152:155], v[174:177], v[48:51]
	v_mfma_f32_16x16x32_bf16 v[36:39], v[144:147], v[182:185], v[36:39]
	v_mfma_f32_16x16x32_bf16 v[32:35], v[152:155], v[182:185], v[32:35]
	v_mfma_f32_16x16x32_bf16 v[20:23], v[144:147], v[190:193], v[20:23]
	v_mfma_f32_16x16x32_bf16 v[16:19], v[152:155], v[190:193], v[16:19]
	v_mfma_f32_16x16x32_bf16 v[4:7], v[144:147], v[198:201], v[4:7]
	v_mfma_f32_16x16x32_bf16 v[0:3], v[152:155], v[198:201], v[0:3]
	v_mfma_f32_16x16x32_bf16 v[52:55], v[148:151], v[178:181], v[52:55]
	v_mfma_f32_16x16x32_bf16 v[48:51], v[170:173], v[178:181], v[48:51]
	v_mfma_f32_16x16x32_bf16 v[36:39], v[148:151], v[186:189], v[36:39]
	v_mfma_f32_16x16x32_bf16 v[32:35], v[170:173], v[186:189], v[32:35]
	v_mfma_f32_16x16x32_bf16 v[20:23], v[148:151], v[194:197], v[20:23]
	v_mfma_f32_16x16x32_bf16 v[16:19], v[170:173], v[194:197], v[16:19]
	v_mfma_f32_16x16x32_bf16 v[4:7], v[148:151], v[202:205], v[4:7]
	v_mfma_f32_16x16x32_bf16 v[0:3], v[170:173], v[202:205], v[0:3]
	s_barrier
	s_setprio 0
	s_add_i32 s83, s83, 2
	s_add_u32 s81, s81, 0x100
	s_addc_u32 s82, s82, 0
	s_cmp_gt_u32 s83, 3
	s_mov_b64 s[8:9], s[6:7]
	s_cbranch_scc0 .LBB0_771
	s_and_b64 vcc, exec, s[30:31]
	s_cbranch_vccz .LBB0_774
	s_barrier

.LBB0_938:
	ds_read_b128 v[128:131], v175
	ds_read_b128 v[132:135], v175 offset:1024
	ds_read_b128 v[136:139], v175 offset:2048
	ds_read_b128 v[140:143], v175 offset:3072
	ds_read_b128 v[144:147], v176
	ds_read_b128 v[148:151], v176 offset:1024
	ds_read_b128 v[168:171], v176 offset:2048
	ds_read_b128 v[182:185], v176 offset:3072
	s_add_u32 s36, s6, 0xfffe0080
	s_addc_u32 s37, s7, -1
	s_cmp_eq_u32 s42, 4
	s_cselect_b32 s39, s9, s37
	s_cselect_b32 s38, s27, s36
	s_cselect_b32 s37, s23, s41
	s_cselect_b32 s36, s35, s40
	v_lshl_add_u64 v[218:219], s[6:7], 0, v[158:159]
	s_add_i32 m0, s48, 0xc000
	ds_read_b128 v[186:189], v177
	ds_read_b128 v[190:193], v177 offset:1024
	ds_read_b128 v[194:197], v177 offset:2048
	ds_read_b128 v[198:201], v177 offset:3072
	ds_read_b128 v[202:205], v177 offset:4096
	ds_read_b128 v[206:209], v177 offset:5120
	ds_read_b128 v[210:213], v177 offset:6144
	ds_read_b128 v[214:217], v177 offset:7168
	global_load_lds_dwordx4 v[218:219], off
	v_lshl_add_u64 v[218:219], s[6:7], 0, v[160:161]
	s_add_i32 m0, s48, 0xe000
	s_nop 0
	global_load_lds_dwordx4 v[218:219], off
	s_waitcnt vmcnt(8)
	s_waitcnt lgkmcnt(0)
	s_setprio 1
	s_barrier
	v_mfma_f32_16x16x32_bf16 v[124:127], v[128:131], v[186:189], v[124:127]
	v_mfma_f32_16x16x32_bf16 v[120:123], v[136:139], v[186:189], v[120:123]
	v_mfma_f32_16x16x32_bf16 v[112:115], v[128:131], v[194:197], v[112:115]
	v_mfma_f32_16x16x32_bf16 v[116:119], v[136:139], v[194:197], v[116:119]
	v_mfma_f32_16x16x32_bf16 v[96:99], v[128:131], v[202:205], v[96:99]
	v_mfma_f32_16x16x32_bf16 v[104:107], v[136:139], v[202:205], v[104:107]
	v_mfma_f32_16x16x32_bf16 v[76:79], v[128:131], v[210:213], v[76:79]
	v_mfma_f32_16x16x32_bf16 v[72:75], v[136:139], v[210:213], v[72:75]
	v_mfma_f32_16x16x32_bf16 v[124:127], v[132:135], v[190:193], v[124:127]
	v_mfma_f32_16x16x32_bf16 v[120:123], v[140:143], v[190:193], v[120:123]
	v_mfma_f32_16x16x32_bf16 v[112:115], v[132:135], v[198:201], v[112:115]
	v_mfma_f32_16x16x32_bf16 v[116:119], v[140:143], v[198:201], v[116:119]
	v_mfma_f32_16x16x32_bf16 v[96:99], v[132:135], v[206:209], v[96:99]
	v_mfma_f32_16x16x32_bf16 v[104:107], v[140:143], v[206:209], v[104:107]
	v_mfma_f32_16x16x32_bf16 v[76:79], v[132:135], v[214:217], v[76:79]
	v_mfma_f32_16x16x32_bf16 v[72:75], v[140:143], v[214:217], v[72:75]
	s_setprio 0
	s_setprio 1
	v_mfma_f32_16x16x32_bf16 v[108:111], v[144:147], v[186:189], v[108:111]
	v_mfma_f32_16x16x32_bf16 v[100:103], v[168:171], v[186:189], v[100:103]
	v_mfma_f32_16x16x32_bf16 v[88:91], v[144:147], v[194:197], v[88:91]
	v_mfma_f32_16x16x32_bf16 v[92:95], v[168:171], v[194:197], v[92:95]
	v_mfma_f32_16x16x32_bf16 v[84:87], v[144:147], v[202:205], v[84:87]
	v_mfma_f32_16x16x32_bf16 v[80:83], v[168:171], v[202:205], v[80:83]
	v_mfma_f32_16x16x32_bf16 v[68:71], v[144:147], v[210:213], v[68:71]
	v_mfma_f32_16x16x32_bf16 v[64:67], v[168:171], v[210:213], v[64:67]
	v_mfma_f32_16x16x32_bf16 v[108:111], v[148:151], v[190:193], v[108:111]
	v_mfma_f32_16x16x32_bf16 v[100:103], v[182:185], v[190:193], v[100:103]
	v_mfma_f32_16x16x32_bf16 v[88:91], v[148:151], v[198:201], v[88:91]
	v_mfma_f32_16x16x32_bf16 v[92:95], v[182:185], v[198:201], v[92:95]
	v_mfma_f32_16x16x32_bf16 v[84:87], v[148:151], v[206:209], v[84:87]
	v_mfma_f32_16x16x32_bf16 v[80:83], v[182:185], v[206:209], v[80:83]
	v_mfma_f32_16x16x32_bf16 v[68:71], v[148:151], v[214:217], v[68:71]
	v_mfma_f32_16x16x32_bf16 v[64:67], v[182:185], v[214:217], v[64:67]
	s_barrier
	s_setprio 0
	s_add_i32 s43, s72, s47
	v_lshl_add_u64 v[218:219], s[36:37], 0, v[152:153]
	s_mov_b32 m0, s43
	ds_read_b128 v[186:189], v177 offset:16384
	ds_read_b128 v[190:193], v177 offset:17408
	ds_read_b128 v[194:197], v177 offset:18432
	ds_read_b128 v[198:201], v177 offset:19456
	ds_read_b128 v[202:205], v177 offset:20480
	ds_read_b128 v[206:209], v177 offset:21504
	ds_read_b128 v[210:213], v177 offset:22528
	ds_read_b128 v[214:217], v177 offset:23552
	global_load_lds_dwordx4 v[218:219], off
	s_add_i32 m0, s43, 0x2000
	s_add_u32 s88, s36, 0x20000
	v_lshl_add_u64 v[220:221], s[36:37], 0, v[154:155]
	s_addc_u32 s89, s37, 0
	s_add_i32 s43, s73, s47
	global_load_lds_dwordx4 v[220:221], off
	v_lshl_add_u64 v[222:223], s[88:89], 0, v[152:153]
	s_mov_b32 m0, s43
	v_lshl_add_u64 v[224:225], s[38:39], 0, v[154:155]
	global_load_lds_dwordx4 v[222:223], off
	v_lshl_add_u64 v[222:223], s[88:89], 0, v[154:155]
	s_add_i32 m0, s43, 0x2000
	s_nop 0
	global_load_lds_dwordx4 v[222:223], off
	v_lshl_add_u64 v[222:223], s[38:39], 0, v[152:153]
	s_mov_b32 m0, s48
	s_nop 0
	global_load_lds_dwordx4 v[222:223], off
	s_mov_b32 m0, s49
	s_nop 0
	global_load_lds_dwordx4 v[224:225], off
	s_waitcnt vmcnt(8)
	s_waitcnt lgkmcnt(0)
	s_setprio 1
	s_barrier
	v_mfma_f32_16x16x32_bf16 v[60:63], v[128:131], v[186:189], v[60:63]
	v_mfma_f32_16x16x32_bf16 v[56:59], v[136:139], v[186:189], v[56:59]
	v_mfma_f32_16x16x32_bf16 v[44:47], v[128:131], v[194:197], v[44:47]
	v_mfma_f32_16x16x32_bf16 v[40:43], v[136:139], v[194:197], v[40:43]
	v_mfma_f32_16x16x32_bf16 v[28:31], v[128:131], v[202:205], v[28:31]
	v_mfma_f32_16x16x32_bf16 v[24:27], v[136:139], v[202:205], v[24:27]
	v_mfma_f32_16x16x32_bf16 v[12:15], v[128:131], v[210:213], v[12:15]
	v_mfma_f32_16x16x32_bf16 v[8:11], v[136:139], v[210:213], v[8:11]
	v_mfma_f32_16x16x32_bf16 v[60:63], v[132:135], v[190:193], v[60:63]
	v_mfma_f32_16x16x32_bf16 v[56:59], v[140:143], v[190:193], v[56:59]
	v_mfma_f32_16x16x32_bf16 v[44:47], v[132:135], v[198:201], v[44:47]
	v_mfma_f32_16x16x32_bf16 v[40:43], v[140:143], v[198:201], v[40:43]
	v_mfma_f32_16x16x32_bf16 v[28:31], v[132:135], v[206:209], v[28:31]
	v_mfma_f32_16x16x32_bf16 v[24:27], v[140:143], v[206:209], v[24:27]
	v_mfma_f32_16x16x32_bf16 v[12:15], v[132:135], v[214:217], v[12:15]
	v_mfma_f32_16x16x32_bf16 v[8:11], v[140:143], v[214:217], v[8:11]
	s_setprio 0
	s_setprio 1
	v_mfma_f32_16x16x32_bf16 v[52:55], v[144:147], v[186:189], v[52:55]
	v_mfma_f32_16x16x32_bf16 v[48:51], v[168:171], v[186:189], v[48:51]
	v_mfma_f32_16x16x32_bf16 v[36:39], v[144:147], v[194:197], v[36:39]
	v_mfma_f32_16x16x32_bf16 v[32:35], v[168:171], v[194:197], v[32:35]
	v_mfma_f32_16x16x32_bf16 v[20:23], v[144:147], v[202:205], v[20:23]
	v_mfma_f32_16x16x32_bf16 v[16:19], v[168:171], v[202:205], v[16:19]
	v_mfma_f32_16x16x32_bf16 v[4:7], v[144:147], v[210:213], v[4:7]
	v_mfma_f32_16x16x32_bf16 v[0:3], v[168:171], v[210:213], v[0:3]
	v_mfma_f32_16x16x32_bf16 v[52:55], v[148:151], v[190:193], v[52:55]
	v_mfma_f32_16x16x32_bf16 v[48:51], v[182:185], v[190:193], v[48:51]
	v_mfma_f32_16x16x32_bf16 v[36:39], v[148:151], v[198:201], v[36:39]
	v_mfma_f32_16x16x32_bf16 v[32:35], v[182:185], v[198:201], v[32:35]
	v_mfma_f32_16x16x32_bf16 v[20:23], v[148:151], v[206:209], v[20:23]
	v_mfma_f32_16x16x32_bf16 v[16:19], v[182:185], v[206:209], v[16:19]
	v_mfma_f32_16x16x32_bf16 v[4:7], v[148:151], v[214:217], v[4:7]
	v_mfma_f32_16x16x32_bf16 v[0:3], v[182:185], v[214:217], v[0:3]
	s_barrier
	s_setprio 0
	s_add_i32 s43, 0, 0x18000
	s_add_i32 s88, 0, 0x1c000
	v_add_u32_e32 v140, s43, v173
	v_add_u32_e32 v156, s88, v173
	ds_read_b128 v[128:131], v140
	ds_read_b128 v[132:135], v140 offset:1024
	ds_read_b128 v[136:139], v140 offset:2048
	ds_read_b128 v[140:143], v140 offset:3072
	ds_read_b128 v[144:147], v156
	ds_read_b128 v[148:151], v156 offset:1024
	ds_read_b128 v[168:171], v156 offset:2048
	ds_read_b128 v[182:185], v156 offset:3072
	s_add_u32 s38, s38, 0x20000
	s_addc_u32 s39, s39, 0
	s_mov_b32 m0, s50
	v_lshl_add_u64 v[226:227], s[38:39], 0, v[152:153]
	ds_read_b128 v[186:189], v177 offset:32768
	ds_read_b128 v[190:193], v177 offset:33792
	ds_read_b128 v[194:197], v177 offset:34816
	ds_read_b128 v[198:201], v177 offset:35840
	ds_read_b128 v[202:205], v177 offset:36864
	ds_read_b128 v[206:209], v177 offset:37888
	ds_read_b128 v[210:213], v177 offset:38912
	ds_read_b128 v[214:217], v177 offset:39936
	global_load_lds_dwordx4 v[226:227], off
	v_lshl_add_u64 v[226:227], s[38:39], 0, v[154:155]
	s_mov_b32 m0, s51
	s_nop 0
	global_load_lds_dwordx4 v[226:227], off
	s_waitcnt vmcnt(8)
	s_waitcnt lgkmcnt(0)
	s_setprio 1
	s_barrier
	v_mfma_f32_16x16x32_bf16 v[124:127], v[128:131], v[186:189], v[124:127]
	v_mfma_f32_16x16x32_bf16 v[120:123], v[136:139], v[186:189], v[120:123]
	v_mfma_f32_16x16x32_bf16 v[112:115], v[128:131], v[194:197], v[112:115]
	v_mfma_f32_16x16x32_bf16 v[116:119], v[136:139], v[194:197], v[116:119]
	v_mfma_f32_16x16x32_bf16 v[96:99], v[128:131], v[202:205], v[96:99]
	v_mfma_f32_16x16x32_bf16 v[104:107], v[136:139], v[202:205], v[104:107]
	v_mfma_f32_16x16x32_bf16 v[76:79], v[128:131], v[210:213], v[76:79]
	v_mfma_f32_16x16x32_bf16 v[72:75], v[136:139], v[210:213], v[72:75]
	v_mfma_f32_16x16x32_bf16 v[124:127], v[132:135], v[190:193], v[124:127]
	v_mfma_f32_16x16x32_bf16 v[120:123], v[140:143], v[190:193], v[120:123]
	v_mfma_f32_16x16x32_bf16 v[112:115], v[132:135], v[198:201], v[112:115]
	v_mfma_f32_16x16x32_bf16 v[116:119], v[140:143], v[198:201], v[116:119]
	v_mfma_f32_16x16x32_bf16 v[96:99], v[132:135], v[206:209], v[96:99]
	v_mfma_f32_16x16x32_bf16 v[104:107], v[140:143], v[206:209], v[104:107]
	v_mfma_f32_16x16x32_bf16 v[76:79], v[132:135], v[214:217], v[76:79]
	v_mfma_f32_16x16x32_bf16 v[72:75], v[140:143], v[214:217], v[72:75]
	s_setprio 0
	s_setprio 1
	v_mfma_f32_16x16x32_bf16 v[108:111], v[144:147], v[186:189], v[108:111]
	v_mfma_f32_16x16x32_bf16 v[100:103], v[168:171], v[186:189], v[100:103]
	v_mfma_f32_16x16x32_bf16 v[88:91], v[144:147], v[194:197], v[88:91]
	v_mfma_f32_16x16x32_bf16 v[92:95], v[168:171], v[194:197], v[92:95]
	v_mfma_f32_16x16x32_bf16 v[84:87], v[144:147], v[202:205], v[84:87]
	v_mfma_f32_16x16x32_bf16 v[80:83], v[168:171], v[202:205], v[80:83]
	v_mfma_f32_16x16x32_bf16 v[68:71], v[144:147], v[210:213], v[68:71]
	v_mfma_f32_16x16x32_bf16 v[64:67], v[168:171], v[210:213], v[64:67]
	v_mfma_f32_16x16x32_bf16 v[108:111], v[148:151], v[190:193], v[108:111]
	v_mfma_f32_16x16x32_bf16 v[100:103], v[182:185], v[190:193], v[100:103]
	v_mfma_f32_16x16x32_bf16 v[88:91], v[148:151], v[198:201], v[88:91]
	v_mfma_f32_16x16x32_bf16 v[92:95], v[182:185], v[198:201], v[92:95]
	v_mfma_f32_16x16x32_bf16 v[84:87], v[148:151], v[206:209], v[84:87]
	v_mfma_f32_16x16x32_bf16 v[80:83], v[182:185], v[206:209], v[80:83]
	v_mfma_f32_16x16x32_bf16 v[68:71], v[148:151], v[214:217], v[68:71]
	v_mfma_f32_16x16x32_bf16 v[64:67], v[182:185], v[214:217], v[64:67]
	s_barrier
	s_setprio 0
	s_add_i32 s38, s43, s47
	v_lshl_add_u64 v[218:219], v[218:219], 0, s[16:17]
	s_mov_b32 m0, s38
	ds_read_b128 v[186:189], v177 offset:49152
	ds_read_b128 v[190:193], v177 offset:50176
	ds_read_b128 v[194:197], v177 offset:51200
	ds_read_b128 v[198:201], v177 offset:52224
	ds_read_b128 v[202:205], v177 offset:53248
	ds_read_b128 v[206:209], v177 offset:54272
	ds_read_b128 v[210:213], v177 offset:55296
	ds_read_b128 v[214:217], v177 offset:56320
	global_load_lds_dwordx4 v[218:219], off
	s_add_i32 m0, s38, 0x2000
	s_add_u32 s36, s36, 0x20080
	v_lshl_add_u64 v[218:219], v[220:221], 0, s[16:17]
	s_addc_u32 s37, s37, 0
	s_add_i32 s38, s88, s47
	global_load_lds_dwordx4 v[218:219], off
	v_lshl_add_u64 v[218:219], s[36:37], 0, v[152:153]
	s_mov_b32 m0, s38
	s_nop 0
	global_load_lds_dwordx4 v[218:219], off
	v_lshl_add_u64 v[218:219], s[36:37], 0, v[154:155]
	s_add_i32 m0, s38, 0x2000
	s_nop 0
	global_load_lds_dwordx4 v[218:219], off
	v_lshl_add_u64 v[218:219], v[222:223], 0, s[16:17]
	s_mov_b32 m0, s61
	s_nop 0
	global_load_lds_dwordx4 v[218:219], off
	v_lshl_add_u64 v[218:219], v[224:225], 0, s[16:17]
	s_mov_b32 m0, s62
	s_nop 0
	global_load_lds_dwordx4 v[218:219], off
	s_waitcnt vmcnt(8)
	s_waitcnt lgkmcnt(0)
	s_setprio 1
	s_barrier
	v_mfma_f32_16x16x32_bf16 v[60:63], v[128:131], v[186:189], v[60:63]
	v_mfma_f32_16x16x32_bf16 v[56:59], v[136:139], v[186:189], v[56:59]
	v_mfma_f32_16x16x32_bf16 v[44:47], v[128:131], v[194:197], v[44:47]
	v_mfma_f32_16x16x32_bf16 v[40:43], v[136:139], v[194:197], v[40:43]
	v_mfma_f32_16x16x32_bf16 v[28:31], v[128:131], v[202:205], v[28:31]
	v_mfma_f32_16x16x32_bf16 v[24:27], v[136:139], v[202:205], v[24:27]
	v_mfma_f32_16x16x32_bf16 v[12:15], v[128:131], v[210:213], v[12:15]
	v_mfma_f32_16x16x32_bf16 v[8:11], v[136:139], v[210:213], v[8:11]
	v_mfma_f32_16x16x32_bf16 v[60:63], v[132:135], v[190:193], v[60:63]
	v_mfma_f32_16x16x32_bf16 v[56:59], v[140:143], v[190:193], v[56:59]
	v_mfma_f32_16x16x32_bf16 v[44:47], v[132:135], v[198:201], v[44:47]
	v_mfma_f32_16x16x32_bf16 v[40:43], v[140:143], v[198:201], v[40:43]
	v_mfma_f32_16x16x32_bf16 v[28:31], v[132:135], v[206:209], v[28:31]
	v_mfma_f32_16x16x32_bf16 v[24:27], v[140:143], v[206:209], v[24:27]
	v_mfma_f32_16x16x32_bf16 v[12:15], v[132:135], v[214:217], v[12:15]
	v_mfma_f32_16x16x32_bf16 v[8:11], v[140:143], v[214:217], v[8:11]
	s_setprio 0
	s_setprio 1
	v_mfma_f32_16x16x32_bf16 v[52:55], v[144:147], v[186:189], v[52:55]
	v_mfma_f32_16x16x32_bf16 v[48:51], v[168:171], v[186:189], v[48:51]
	v_mfma_f32_16x16x32_bf16 v[36:39], v[144:147], v[194:197], v[36:39]
	v_mfma_f32_16x16x32_bf16 v[32:35], v[168:171], v[194:197], v[32:35]
	v_mfma_f32_16x16x32_bf16 v[20:23], v[144:147], v[202:205], v[20:23]
	v_mfma_f32_16x16x32_bf16 v[16:19], v[168:171], v[202:205], v[16:19]
	v_mfma_f32_16x16x32_bf16 v[4:7], v[144:147], v[210:213], v[4:7]
	v_mfma_f32_16x16x32_bf16 v[0:3], v[168:171], v[210:213], v[0:3]
	v_mfma_f32_16x16x32_bf16 v[52:55], v[148:151], v[190:193], v[52:55]
	v_mfma_f32_16x16x32_bf16 v[48:51], v[182:185], v[190:193], v[48:51]
	v_mfma_f32_16x16x32_bf16 v[36:39], v[148:151], v[198:201], v[36:39]
	v_mfma_f32_16x16x32_bf16 v[32:35], v[182:185], v[198:201], v[32:35]
	v_mfma_f32_16x16x32_bf16 v[20:23], v[148:151], v[206:209], v[20:23]
	v_mfma_f32_16x16x32_bf16 v[16:19], v[182:185], v[206:209], v[16:19]
	v_mfma_f32_16x16x32_bf16 v[4:7], v[148:151], v[214:217], v[4:7]
	v_mfma_f32_16x16x32_bf16 v[0:3], v[182:185], v[214:217], v[0:3]
	s_barrier
	s_setprio 0
	s_add_i32 s42, s42, 2
	s_add_u32 s6, s6, 0x100
	s_addc_u32 s7, s7, 0
	s_add_u32 s40, s40, 0x100
	s_addc_u32 s41, s41, 0
	s_cmp_gt_u32 s42, 5
	s_cbranch_scc0 .LBB0_938
	s_and_b64 vcc, exec, s[18:19]
	s_cbranch_vccz .LBB0_941
	s_barrier
